# v22 + K-loop back edge rotated: counter/pointer increments and next-iteration scalar setup moved before the closing barrier
# baseline (speedup 1.0000x reference)
; #define PG8_STAGE(bufoff, gbase, voff) do { _Pragma("unroll") for (int _i = 0; _i < 2; ++_i) \
;         __builtin_amdgcn_global_load_lds((const unsigned*)((const char*)(gbase) + (voff)[_i]), (PG8_LAS unsigned*)(lds + (bufoff) + ldsw + _i * 8192), 16, 0, 0); } while (0)
; #define PG8_LDA(dst, b, h) do { _Pragma("unroll") for (int m = 0; m < 4; ++m) _Pragma("unroll") for (int k = 0; k < 2; ++k) dst[m][k] = *(const PG8_LAS bf16x8*)(lds + PG8_SA(b, h) + aoff + m * 2048 + k * 1024); } while (0)
; #define PG8_LDB(dst, b, h) do { _Pragma("unroll") for (int n = 0; n < 2; ++n) _Pragma("unroll") for (int k = 0; k < 2; ++k) dst[n][k] = *(const PG8_LAS bf16x8*)(lds + PG8_SB(b, h) + boff + n * 2048 + k * 1024); } while (0)
; #define PG8_MMA(ai, bj, At, Bt) do { __builtin_amdgcn_s_setprio(1); _Pragma("unroll") for (int m = 0; m < 4; ++m) _Pragma("unroll") for (int n = 0; n < 2; ++n) _Pragma("unroll") for (int k = 0; k < 2; ++k) \
;         acc[ai][bj][m][n] = __builtin_amdgcn_mfma_f32_16x16x32_bf16(Bt[n][k], At[m][k], acc[ai][bj][m][n], 0, 0, 0); __builtin_amdgcn_s_setprio(0); } while (0)
; #define PG8_WAIT_V(n) asm volatile("s_waitcnt vmcnt(" #n ")" ::: "memory")
; #define PG8_WAIT_L(n) asm volatile("s_waitcnt lgkmcnt(" #n ")" ::: "memory")
; #define PG8_BAR __builtin_amdgcn_s_barrier()
; #define PG8_SCHED __builtin_amdgcn_sched_barrier(0)
; template <class Epi, class Sched, bool ALIGN_EPI = false, bool SP2 = false>
; __device__ __forceinline__ void gemm_phase(PG8_LAS unsigned char* lds, const Gemm g, const Sched& S, const Epi& E) {
;     ...
;         for (int t = 0; t < nt; t += 2) {
;             const bool last = (t == nt - 2);
;             const char* a1 = cA + (size_t)(t + 1) * kstep;
;             const char* a2 = last ? nA : cA + (size_t)(t + 2) * kstep; const char* b2 = last ? nB : cB + (size_t)(t + 2) * kstep;
;             const char* a3 = a2 + kstep; const char* b3 = b2 + kstep;
;             if (last && has_next) S.a_ready(nxt);
;             if constexpr (SP2) {
;             PG8_LDB(B0, 0, 0); PG8_LDB(B1, 0, 1); PG8_SCHED; PG8_LDA(At, 0, 0); PG8_STAGE(PG8_SA(1, 1), a1 + hstep, voffA);
;             PG8_WAIT_V(8); PG8_WAIT_L(0); PG8_BAR; PG8_MMA(0, 0, At, B0); PG8_MMA(0, 1, At, B1); PG8_BAR; PG8_SCHED;
.LBB0_368:
	s_add_u32 s18, s16, 0xfffc0080
	s_addc_u32 s19, s17, -1
	s_add_i32 s56, 0, 0x10000
	s_cmp_eq_u32 s55, 12
	s_cselect_b32 s21, s11, s19
	s_cselect_b32 s20, s50, s18
	s_cselect_b32 s19, s9, s53
	s_cselect_b32 s18, s51, s52
	s_add_i32 s58, 0, 0x14000
.Lrot_368:
	v_add_u32_e32 v140, s56, v143
	ds_read_b128 v[154:157], v140
	ds_read_b128 v[158:161], v140 offset:1024
	ds_read_b128 v[162:165], v140 offset:2048
	ds_read_b128 v[166:169], v140 offset:3072
	v_add_u32_e32 v140, s58, v143
	ds_read_b128 v[170:173], v140
	ds_read_b128 v[174:177], v140 offset:1024
	ds_read_b128 v[178:181], v140 offset:2048
	ds_read_b128 v[200:203], v140 offset:3072
	v_lshl_add_u64 v[140:141], s[16:17], 0, v[136:137]
	s_add_i32 m0, s25, 0xc000
	ds_read_b128 v[204:207], v145
	ds_read_b128 v[208:211], v145 offset:1024
	ds_read_b128 v[212:215], v145 offset:2048
	ds_read_b128 v[216:219], v145 offset:3072
	ds_read_b128 v[220:223], v145 offset:4096
	ds_read_b128 v[224:227], v145 offset:5120
	ds_read_b128 v[228:231], v145 offset:6144
	ds_read_b128 v[232:235], v145 offset:7168
	global_load_lds_dwordx4 v[140:141], off
	v_lshl_add_u64 v[140:141], s[16:17], 0, v[138:139]
	s_add_i32 m0, s25, 0xe000
	s_nop 0
	global_load_lds_dwordx4 v[140:141], off
	s_waitcnt vmcnt(8)
	s_waitcnt lgkmcnt(0)
	s_barrier
	s_setprio 1
	s_waitcnt lgkmcnt(0)
	v_mfma_f32_16x16x32_bf16 v[122:125], v[154:157], v[204:207], v[122:125]
	v_mfma_f32_16x16x32_bf16 v[114:117], v[162:165], v[204:207], v[114:117]
	v_mfma_f32_16x16x32_bf16 v[106:109], v[154:157], v[212:215], v[106:109]
	v_mfma_f32_16x16x32_bf16 v[98:101], v[162:165], v[212:215], v[98:101]
	v_mfma_f32_16x16x32_bf16 v[90:93], v[154:157], v[220:223], v[90:93]
	v_mfma_f32_16x16x32_bf16 v[82:85], v[162:165], v[220:223], v[82:85]
	v_mfma_f32_16x16x32_bf16 v[74:77], v[154:157], v[228:231], v[74:77]
	v_mfma_f32_16x16x32_bf16 v[66:69], v[162:165], v[228:231], v[66:69]
	v_mfma_f32_16x16x32_bf16 v[122:125], v[158:161], v[208:211], v[122:125]
	v_mfma_f32_16x16x32_bf16 v[114:117], v[166:169], v[208:211], v[114:117]
	v_mfma_f32_16x16x32_bf16 v[106:109], v[158:161], v[216:219], v[106:109]
	v_mfma_f32_16x16x32_bf16 v[98:101], v[166:169], v[216:219], v[98:101]
	v_mfma_f32_16x16x32_bf16 v[90:93], v[158:161], v[224:227], v[90:93]
	v_mfma_f32_16x16x32_bf16 v[82:85], v[166:169], v[224:227], v[82:85]
	v_mfma_f32_16x16x32_bf16 v[74:77], v[158:161], v[232:235], v[74:77]
	v_mfma_f32_16x16x32_bf16 v[66:69], v[166:169], v[232:235], v[66:69]
	s_setprio 0
	s_setprio 1
	v_mfma_f32_16x16x32_bf16 v[126:129], v[170:173], v[204:207], v[126:129]
	v_mfma_f32_16x16x32_bf16 v[118:121], v[178:181], v[204:207], v[118:121]
	v_mfma_f32_16x16x32_bf16 v[110:113], v[170:173], v[212:215], v[110:113]
	v_mfma_f32_16x16x32_bf16 v[102:105], v[178:181], v[212:215], v[102:105]
	v_mfma_f32_16x16x32_bf16 v[94:97], v[170:173], v[220:223], v[94:97]
	v_mfma_f32_16x16x32_bf16 v[86:89], v[178:181], v[220:223], v[86:89]
	v_mfma_f32_16x16x32_bf16 v[78:81], v[170:173], v[228:231], v[78:81]
	v_mfma_f32_16x16x32_bf16 v[70:73], v[178:181], v[228:231], v[70:73]
	v_mfma_f32_16x16x32_bf16 v[126:129], v[174:177], v[208:211], v[126:129]
	v_mfma_f32_16x16x32_bf16 v[118:121], v[200:203], v[208:211], v[118:121]
	v_mfma_f32_16x16x32_bf16 v[110:113], v[174:177], v[216:219], v[110:113]
	v_mfma_f32_16x16x32_bf16 v[102:105], v[200:203], v[216:219], v[102:105]
	v_mfma_f32_16x16x32_bf16 v[94:97], v[174:177], v[224:227], v[94:97]
	v_mfma_f32_16x16x32_bf16 v[86:89], v[200:203], v[224:227], v[86:89]
	v_mfma_f32_16x16x32_bf16 v[78:81], v[174:177], v[232:235], v[78:81]
	v_mfma_f32_16x16x32_bf16 v[70:73], v[200:203], v[232:235], v[70:73]
	s_setprio 0
	s_barrier
	s_add_i32 s56, s56, s24
	v_lshl_add_u64 v[140:141], s[18:19], 0, v[0:1]
	s_mov_b32 m0, s56
	ds_read_b128 v[204:207], v145 offset:16384
	ds_read_b128 v[208:211], v145 offset:17408
	ds_read_b128 v[212:215], v145 offset:18432
	ds_read_b128 v[216:219], v145 offset:19456
	ds_read_b128 v[220:223], v145 offset:20480
	ds_read_b128 v[224:227], v145 offset:21504
	ds_read_b128 v[228:231], v145 offset:22528
	ds_read_b128 v[232:235], v145 offset:23552
	global_load_lds_dwordx4 v[140:141], off
	s_add_i32 m0, s56, 0x2000
	s_add_u32 s56, s18, 0x40000
	v_lshl_add_u64 v[146:147], s[18:19], 0, v[130:131]
	s_addc_u32 s57, s19, 0
	s_add_i32 s58, s58, s24
	global_load_lds_dwordx4 v[146:147], off
	v_lshl_add_u64 v[148:149], s[56:57], 0, v[0:1]
	s_mov_b32 m0, s58
	v_lshl_add_u64 v[236:237], s[20:21], 0, v[132:133]
	global_load_lds_dwordx4 v[148:149], off
	v_lshl_add_u64 v[148:149], s[56:57], 0, v[130:131]
	s_add_i32 m0, s58, 0x2000
	s_nop 0
	global_load_lds_dwordx4 v[148:149], off
	v_lshl_add_u64 v[148:149], s[20:21], 0, v[134:135]
	s_mov_b32 m0, s25
	s_nop 0
	global_load_lds_dwordx4 v[148:149], off
	s_mov_b32 m0, s26
	s_nop 0
	global_load_lds_dwordx4 v[236:237], off
	s_waitcnt vmcnt(8)
	s_waitcnt lgkmcnt(0)
	s_barrier
; #define PG8_STAGE(bufoff, gbase, voff) do { _Pragma("unroll") for (int _i = 0; _i < 2; ++_i) \
;         __builtin_amdgcn_global_load_lds((const unsigned*)((const char*)(gbase) + (voff)[_i]), (PG8_LAS unsigned*)(lds + (bufoff) + ldsw + _i * 8192), 16, 0, 0); } while (0)
; #define PG8_LDA(dst, b, h) do { _Pragma("unroll") for (int m = 0; m < 4; ++m) _Pragma("unroll") for (int k = 0; k < 2; ++k) dst[m][k] = *(const PG8_LAS bf16x8*)(lds + PG8_SA(b, h) + aoff + m * 2048 + k * 1024); } while (0)
; #define PG8_LDB(dst, b, h) do { _Pragma("unroll") for (int n = 0; n < 2; ++n) _Pragma("unroll") for (int k = 0; k < 2; ++k) dst[n][k] = *(const PG8_LAS bf16x8*)(lds + PG8_SB(b, h) + boff + n * 2048 + k * 1024); } while (0)
; #define PG8_MMA(ai, bj, At, Bt) do { __builtin_amdgcn_s_setprio(1); _Pragma("unroll") for (int m = 0; m < 4; ++m) _Pragma("unroll") for (int n = 0; n < 2; ++n) _Pragma("unroll") for (int k = 0; k < 2; ++k) \
;         acc[ai][bj][m][n] = __builtin_amdgcn_mfma_f32_16x16x32_bf16(Bt[n][k], At[m][k], acc[ai][bj][m][n], 0, 0, 0); __builtin_amdgcn_s_setprio(0); } while (0)
; #define PG8_WAIT_V(n) asm volatile("s_waitcnt vmcnt(" #n ")" ::: "memory")
; #define PG8_WAIT_L(n) asm volatile("s_waitcnt lgkmcnt(" #n ")" ::: "memory")
; #define PG8_BAR __builtin_amdgcn_s_barrier()
; #define PG8_SCHED __builtin_amdgcn_sched_barrier(0)
; template <class Epi, class Sched, bool ALIGN_EPI = false, bool SP2 = false>
; __device__ __forceinline__ void gemm_phase(PG8_LAS unsigned char* lds, const Gemm g, const Sched& S, const Epi& E) {
;     ...
;             PG8_WAIT_V(8); PG8_WAIT_L(0); PG8_BAR; PG8_MMA(0, 0, At, B0); PG8_MMA(0, 1, At, B1); PG8_BAR; PG8_SCHED;
;             PG8_LDA(At, 0, 1); PG8_STAGE(PG8_SB(0, 0), b2, voffB); PG8_STAGE(PG8_SB(0, 1), b2 + hstep, voffB); PG8_STAGE(PG8_SA(0, 0), a2, voffA);
;             PG8_WAIT_V(8); PG8_WAIT_L(0); PG8_BAR; PG8_MMA(1, 0, At, B0); PG8_MMA(1, 1, At, B1); PG8_BAR; PG8_SCHED;
;             PG8_LDB(B0, 1, 0); PG8_LDB(B1, 1, 1); PG8_SCHED; PG8_LDA(At, 1, 0); PG8_STAGE(PG8_SA(0, 1), a2 + hstep, voffA);
;             PG8_WAIT_V(8); PG8_WAIT_L(0); PG8_BAR; PG8_MMA(0, 0, At, B0); PG8_MMA(0, 1, At, B1); PG8_BAR; PG8_SCHED;
	s_setprio 1
	s_waitcnt lgkmcnt(0)
	v_mfma_f32_16x16x32_bf16 v[58:61], v[154:157], v[204:207], v[58:61]
	v_mfma_f32_16x16x32_bf16 v[50:53], v[162:165], v[204:207], v[50:53]
	v_mfma_f32_16x16x32_bf16 v[42:45], v[154:157], v[212:215], v[42:45]
	v_mfma_f32_16x16x32_bf16 v[34:37], v[162:165], v[212:215], v[34:37]
	v_mfma_f32_16x16x32_bf16 v[26:29], v[154:157], v[220:223], v[26:29]
	v_mfma_f32_16x16x32_bf16 v[18:21], v[162:165], v[220:223], v[18:21]
	v_mfma_f32_16x16x32_bf16 v[10:13], v[154:157], v[228:231], v[10:13]
	v_mfma_f32_16x16x32_bf16 v[2:5], v[162:165], v[228:231], v[2:5]
	v_mfma_f32_16x16x32_bf16 v[58:61], v[158:161], v[208:211], v[58:61]
	v_mfma_f32_16x16x32_bf16 v[50:53], v[166:169], v[208:211], v[50:53]
	v_mfma_f32_16x16x32_bf16 v[42:45], v[158:161], v[216:219], v[42:45]
	v_mfma_f32_16x16x32_bf16 v[34:37], v[166:169], v[216:219], v[34:37]
	v_mfma_f32_16x16x32_bf16 v[26:29], v[158:161], v[224:227], v[26:29]
	v_mfma_f32_16x16x32_bf16 v[18:21], v[166:169], v[224:227], v[18:21]
	v_mfma_f32_16x16x32_bf16 v[10:13], v[158:161], v[232:235], v[10:13]
	v_mfma_f32_16x16x32_bf16 v[2:5], v[166:169], v[232:235], v[2:5]
	s_setprio 0
	s_setprio 1
	v_mfma_f32_16x16x32_bf16 v[62:65], v[170:173], v[204:207], v[62:65]
	v_mfma_f32_16x16x32_bf16 v[54:57], v[178:181], v[204:207], v[54:57]
	v_mfma_f32_16x16x32_bf16 v[46:49], v[170:173], v[212:215], v[46:49]
	v_mfma_f32_16x16x32_bf16 v[38:41], v[178:181], v[212:215], v[38:41]
	v_mfma_f32_16x16x32_bf16 v[30:33], v[170:173], v[220:223], v[30:33]
	v_mfma_f32_16x16x32_bf16 v[22:25], v[178:181], v[220:223], v[22:25]
	v_mfma_f32_16x16x32_bf16 v[14:17], v[170:173], v[228:231], v[14:17]
	v_mfma_f32_16x16x32_bf16 v[6:9], v[178:181], v[228:231], v[6:9]
	v_mfma_f32_16x16x32_bf16 v[62:65], v[174:177], v[208:211], v[62:65]
	v_mfma_f32_16x16x32_bf16 v[54:57], v[200:203], v[208:211], v[54:57]
	v_mfma_f32_16x16x32_bf16 v[46:49], v[174:177], v[216:219], v[46:49]
	v_mfma_f32_16x16x32_bf16 v[38:41], v[200:203], v[216:219], v[38:41]
	v_mfma_f32_16x16x32_bf16 v[30:33], v[174:177], v[224:227], v[30:33]
	v_mfma_f32_16x16x32_bf16 v[22:25], v[200:203], v[224:227], v[22:25]
	v_mfma_f32_16x16x32_bf16 v[14:17], v[174:177], v[232:235], v[14:17]
	v_mfma_f32_16x16x32_bf16 v[6:9], v[200:203], v[232:235], v[6:9]
	s_setprio 0
	s_barrier
	s_add_i32 s56, 0, 0x18000
	s_add_i32 s57, 0, 0x1c000
	v_add_u32_e32 v166, s56, v143
	v_add_u32_e32 v200, s57, v143
	ds_read_b128 v[154:157], v166
	ds_read_b128 v[158:161], v166 offset:1024
	ds_read_b128 v[162:165], v166 offset:2048
	ds_read_b128 v[166:169], v166 offset:3072
	ds_read_b128 v[170:173], v200
	ds_read_b128 v[174:177], v200 offset:1024
	ds_read_b128 v[178:181], v200 offset:2048
	ds_read_b128 v[200:203], v200 offset:3072
	s_add_u32 s20, s20, 0x40000
	s_addc_u32 s21, s21, 0
	s_mov_b32 m0, s27
	v_lshl_add_u64 v[238:239], s[20:21], 0, v[134:135]
	ds_read_b128 v[204:207], v145 offset:32768
	ds_read_b128 v[208:211], v145 offset:33792
	ds_read_b128 v[212:215], v145 offset:34816
	ds_read_b128 v[216:219], v145 offset:35840
	ds_read_b128 v[220:223], v145 offset:36864
	ds_read_b128 v[224:227], v145 offset:37888
	ds_read_b128 v[228:231], v145 offset:38912
	ds_read_b128 v[232:235], v145 offset:39936
	global_load_lds_dwordx4 v[238:239], off
	v_lshl_add_u64 v[238:239], s[20:21], 0, v[132:133]
	s_mov_b32 m0, s28
	s_nop 0
	global_load_lds_dwordx4 v[238:239], off
	s_waitcnt vmcnt(8)
	s_waitcnt lgkmcnt(0)
	s_barrier
	s_setprio 1
	s_waitcnt lgkmcnt(0)
	v_mfma_f32_16x16x32_bf16 v[122:125], v[154:157], v[204:207], v[122:125]
	v_mfma_f32_16x16x32_bf16 v[114:117], v[162:165], v[204:207], v[114:117]
	v_mfma_f32_16x16x32_bf16 v[106:109], v[154:157], v[212:215], v[106:109]
	v_mfma_f32_16x16x32_bf16 v[98:101], v[162:165], v[212:215], v[98:101]
	v_mfma_f32_16x16x32_bf16 v[90:93], v[154:157], v[220:223], v[90:93]
	v_mfma_f32_16x16x32_bf16 v[82:85], v[162:165], v[220:223], v[82:85]
	v_mfma_f32_16x16x32_bf16 v[74:77], v[154:157], v[228:231], v[74:77]
	v_mfma_f32_16x16x32_bf16 v[66:69], v[162:165], v[228:231], v[66:69]
	v_mfma_f32_16x16x32_bf16 v[122:125], v[158:161], v[208:211], v[122:125]
	v_mfma_f32_16x16x32_bf16 v[114:117], v[166:169], v[208:211], v[114:117]
	v_mfma_f32_16x16x32_bf16 v[106:109], v[158:161], v[216:219], v[106:109]
	v_mfma_f32_16x16x32_bf16 v[98:101], v[166:169], v[216:219], v[98:101]
	v_mfma_f32_16x16x32_bf16 v[90:93], v[158:161], v[224:227], v[90:93]
	v_mfma_f32_16x16x32_bf16 v[82:85], v[166:169], v[224:227], v[82:85]
	v_mfma_f32_16x16x32_bf16 v[74:77], v[158:161], v[232:235], v[74:77]
	v_mfma_f32_16x16x32_bf16 v[66:69], v[166:169], v[232:235], v[66:69]
	s_setprio 0
	s_setprio 1
	v_mfma_f32_16x16x32_bf16 v[126:129], v[170:173], v[204:207], v[126:129]
	v_mfma_f32_16x16x32_bf16 v[118:121], v[178:181], v[204:207], v[118:121]
	v_mfma_f32_16x16x32_bf16 v[110:113], v[170:173], v[212:215], v[110:113]
	v_mfma_f32_16x16x32_bf16 v[102:105], v[178:181], v[212:215], v[102:105]
	v_mfma_f32_16x16x32_bf16 v[94:97], v[170:173], v[220:223], v[94:97]
	v_mfma_f32_16x16x32_bf16 v[86:89], v[178:181], v[220:223], v[86:89]
	v_mfma_f32_16x16x32_bf16 v[78:81], v[170:173], v[228:231], v[78:81]
	v_mfma_f32_16x16x32_bf16 v[70:73], v[178:181], v[228:231], v[70:73]
	v_mfma_f32_16x16x32_bf16 v[126:129], v[174:177], v[208:211], v[126:129]
	v_mfma_f32_16x16x32_bf16 v[118:121], v[200:203], v[208:211], v[118:121]
	v_mfma_f32_16x16x32_bf16 v[110:113], v[174:177], v[216:219], v[110:113]
	v_mfma_f32_16x16x32_bf16 v[102:105], v[200:203], v[216:219], v[102:105]
	v_mfma_f32_16x16x32_bf16 v[94:97], v[174:177], v[224:227], v[94:97]
	v_mfma_f32_16x16x32_bf16 v[86:89], v[200:203], v[224:227], v[86:89]
	v_mfma_f32_16x16x32_bf16 v[78:81], v[174:177], v[232:235], v[78:81]
	v_mfma_f32_16x16x32_bf16 v[70:73], v[200:203], v[232:235], v[70:73]
	s_setprio 0
	s_barrier
; #define PG8_STAGE(bufoff, gbase, voff) do { _Pragma("unroll") for (int _i = 0; _i < 2; ++_i) \
;         __builtin_amdgcn_global_load_lds((const unsigned*)((const char*)(gbase) + (voff)[_i]), (PG8_LAS unsigned*)(lds + (bufoff) + ldsw + _i * 8192), 16, 0, 0); } while (0)
; #define PG8_LDA(dst, b, h) do { _Pragma("unroll") for (int m = 0; m < 4; ++m) _Pragma("unroll") for (int k = 0; k < 2; ++k) dst[m][k] = *(const PG8_LAS bf16x8*)(lds + PG8_SA(b, h) + aoff + m * 2048 + k * 1024); } while (0)
; #define PG8_MMA(ai, bj, At, Bt) do { __builtin_amdgcn_s_setprio(1); _Pragma("unroll") for (int m = 0; m < 4; ++m) _Pragma("unroll") for (int n = 0; n < 2; ++n) _Pragma("unroll") for (int k = 0; k < 2; ++k) \
;         acc[ai][bj][m][n] = __builtin_amdgcn_mfma_f32_16x16x32_bf16(Bt[n][k], At[m][k], acc[ai][bj][m][n], 0, 0, 0); __builtin_amdgcn_s_setprio(0); } while (0)
; #define PG8_WAIT_V(n) asm volatile("s_waitcnt vmcnt(" #n ")" ::: "memory")
; #define PG8_WAIT_L(n) asm volatile("s_waitcnt lgkmcnt(" #n ")" ::: "memory")
; #define PG8_BAR __builtin_amdgcn_s_barrier()
; #define PG8_SCHED __builtin_amdgcn_sched_barrier(0)
; template <class Epi, class Sched, bool ALIGN_EPI = false, bool SP2 = false>
; __device__ __forceinline__ void gemm_phase(PG8_LAS unsigned char* lds, const Gemm g, const Sched& S, const Epi& E) {
;     ...
;         for (int t = 0; t < nt; t += 2) {
;             const bool last = (t == nt - 2);
;             const char* a1 = cA + (size_t)(t + 1) * kstep;
;             const char* a2 = last ? nA : cA + (size_t)(t + 2) * kstep; const char* b2 = last ? nB : cB + (size_t)(t + 2) * kstep;
;             const char* a3 = a2 + kstep; const char* b3 = b2 + kstep;
;             if (last && has_next) S.a_ready(nxt);
;     ...
;             PG8_WAIT_V(8); PG8_WAIT_L(0); PG8_BAR; PG8_MMA(0, 0, At, B0); PG8_MMA(0, 1, At, B1); PG8_BAR; PG8_SCHED;
;             PG8_LDA(At, 1, 1); PG8_STAGE(PG8_SB(1, 0), b3, voffB); PG8_STAGE(PG8_SB(1, 1), b3 + hstep, voffB); PG8_STAGE(PG8_SA(1, 0), a3, voffA);
;             PG8_WAIT_V(8); PG8_WAIT_L(0); PG8_BAR; PG8_MMA(1, 0, At, B0); PG8_MMA(1, 1, At, B1); PG8_BAR; PG8_SCHED;
	s_add_i32 s20, s56, s24
	v_lshl_add_u64 v[140:141], v[140:141], 0, s[38:39]
	s_mov_b32 m0, s20
	ds_read_b128 v[204:207], v145 offset:49152
	ds_read_b128 v[208:211], v145 offset:50176
	ds_read_b128 v[212:215], v145 offset:51200
	ds_read_b128 v[216:219], v145 offset:52224
	ds_read_b128 v[220:223], v145 offset:53248
	ds_read_b128 v[224:227], v145 offset:54272
	ds_read_b128 v[228:231], v145 offset:55296
	ds_read_b128 v[232:235], v145 offset:56320
	global_load_lds_dwordx4 v[140:141], off
	s_add_i32 m0, s20, 0x2000
	s_add_u32 s18, s18, 0x40080
	v_lshl_add_u64 v[140:141], v[146:147], 0, s[38:39]
	s_addc_u32 s19, s19, 0
	s_add_i32 s20, s57, s24
	global_load_lds_dwordx4 v[140:141], off
	v_lshl_add_u64 v[140:141], s[18:19], 0, v[0:1]
	s_mov_b32 m0, s20
	s_nop 0
	global_load_lds_dwordx4 v[140:141], off
	v_lshl_add_u64 v[140:141], s[18:19], 0, v[130:131]
	s_add_i32 m0, s20, 0x2000
	s_nop 0
	global_load_lds_dwordx4 v[140:141], off
	v_lshl_add_u64 v[140:141], v[148:149], 0, s[38:39]
	s_mov_b32 m0, s29
	s_nop 0
	global_load_lds_dwordx4 v[140:141], off
	v_lshl_add_u64 v[140:141], v[236:237], 0, s[38:39]
	s_mov_b32 m0, s30
	s_nop 0
	global_load_lds_dwordx4 v[140:141], off
	s_waitcnt vmcnt(8)
	s_waitcnt lgkmcnt(0)
	s_barrier
	s_setprio 1
	s_waitcnt lgkmcnt(0)
	v_mfma_f32_16x16x32_bf16 v[58:61], v[154:157], v[204:207], v[58:61]
	v_mfma_f32_16x16x32_bf16 v[50:53], v[162:165], v[204:207], v[50:53]
	v_mfma_f32_16x16x32_bf16 v[42:45], v[154:157], v[212:215], v[42:45]
	v_mfma_f32_16x16x32_bf16 v[34:37], v[162:165], v[212:215], v[34:37]
	v_mfma_f32_16x16x32_bf16 v[26:29], v[154:157], v[220:223], v[26:29]
	v_mfma_f32_16x16x32_bf16 v[18:21], v[162:165], v[220:223], v[18:21]
	v_mfma_f32_16x16x32_bf16 v[10:13], v[154:157], v[228:231], v[10:13]
	v_mfma_f32_16x16x32_bf16 v[2:5], v[162:165], v[228:231], v[2:5]
	v_mfma_f32_16x16x32_bf16 v[58:61], v[158:161], v[208:211], v[58:61]
	v_mfma_f32_16x16x32_bf16 v[50:53], v[166:169], v[208:211], v[50:53]
	v_mfma_f32_16x16x32_bf16 v[42:45], v[158:161], v[216:219], v[42:45]
	v_mfma_f32_16x16x32_bf16 v[34:37], v[166:169], v[216:219], v[34:37]
	v_mfma_f32_16x16x32_bf16 v[26:29], v[158:161], v[224:227], v[26:29]
	v_mfma_f32_16x16x32_bf16 v[18:21], v[166:169], v[224:227], v[18:21]
	v_mfma_f32_16x16x32_bf16 v[10:13], v[158:161], v[232:235], v[10:13]
	v_mfma_f32_16x16x32_bf16 v[2:5], v[166:169], v[232:235], v[2:5]
	s_setprio 0
	s_setprio 1
	v_mfma_f32_16x16x32_bf16 v[62:65], v[170:173], v[204:207], v[62:65]
	v_mfma_f32_16x16x32_bf16 v[54:57], v[178:181], v[204:207], v[54:57]
	v_mfma_f32_16x16x32_bf16 v[46:49], v[170:173], v[212:215], v[46:49]
	v_mfma_f32_16x16x32_bf16 v[38:41], v[178:181], v[212:215], v[38:41]
	v_mfma_f32_16x16x32_bf16 v[30:33], v[170:173], v[220:223], v[30:33]
	v_mfma_f32_16x16x32_bf16 v[22:25], v[178:181], v[220:223], v[22:25]
	v_mfma_f32_16x16x32_bf16 v[14:17], v[170:173], v[228:231], v[14:17]
	v_mfma_f32_16x16x32_bf16 v[6:9], v[178:181], v[228:231], v[6:9]
	v_mfma_f32_16x16x32_bf16 v[62:65], v[174:177], v[208:211], v[62:65]
	v_mfma_f32_16x16x32_bf16 v[54:57], v[200:203], v[208:211], v[54:57]
	v_mfma_f32_16x16x32_bf16 v[46:49], v[174:177], v[216:219], v[46:49]
	v_mfma_f32_16x16x32_bf16 v[38:41], v[200:203], v[216:219], v[38:41]
	v_mfma_f32_16x16x32_bf16 v[30:33], v[174:177], v[224:227], v[30:33]
	v_mfma_f32_16x16x32_bf16 v[22:25], v[200:203], v[224:227], v[22:25]
	v_mfma_f32_16x16x32_bf16 v[14:17], v[174:177], v[232:235], v[14:17]
	v_mfma_f32_16x16x32_bf16 v[6:9], v[200:203], v[232:235], v[6:9]
	s_setprio 0
	s_add_i32 s55, s55, 2
	s_add_u32 s16, s16, 0x100
	s_addc_u32 s17, s17, 0
	s_add_u32 s52, s52, 0x100
	s_addc_u32 s53, s53, 0
	s_add_u32 s18, s16, 0xfffc0080
	s_addc_u32 s19, s17, -1
	s_add_i32 s56, 0, 0x10000
	s_cmp_eq_u32 s55, 12
	s_cselect_b32 s21, s11, s19
	s_cselect_b32 s20, s50, s18
	s_cselect_b32 s19, s9, s53
	s_cselect_b32 s18, s51, s52
	s_add_i32 s58, 0, 0x14000
	s_barrier
	s_cmp_gt_u32 s55, 13
	s_cbranch_scc0 .Lrot_368
	s_and_b64 vcc, exec, s[6:7]
	s_cbranch_vccz .LBB0_371
	s_barrier

; #define PG8_STAGE(bufoff, gbase, voff) do { _Pragma("unroll") for (int _i = 0; _i < 2; ++_i) \
;         __builtin_amdgcn_global_load_lds((const unsigned*)((const char*)(gbase) + (voff)[_i]), (PG8_LAS unsigned*)(lds + (bufoff) + ldsw + _i * 8192), 16, 0, 0); } while (0)
; #define PG8_LDA(dst, b, h) do { _Pragma("unroll") for (int m = 0; m < 4; ++m) _Pragma("unroll") for (int k = 0; k < 2; ++k) dst[m][k] = *(const PG8_LAS bf16x8*)(lds + PG8_SA(b, h) + aoff + m * 2048 + k * 1024); } while (0)
; #define PG8_LDB(dst, b, h) do { _Pragma("unroll") for (int n = 0; n < 2; ++n) _Pragma("unroll") for (int k = 0; k < 2; ++k) dst[n][k] = *(const PG8_LAS bf16x8*)(lds + PG8_SB(b, h) + boff + n * 2048 + k * 1024); } while (0)
; #define PG8_MMA(ai, bj, At, Bt) do { __builtin_amdgcn_s_setprio(1); _Pragma("unroll") for (int m = 0; m < 4; ++m) _Pragma("unroll") for (int n = 0; n < 2; ++n) _Pragma("unroll") for (int k = 0; k < 2; ++k) \
;         acc[ai][bj][m][n] = __builtin_amdgcn_mfma_f32_16x16x32_bf16(Bt[n][k], At[m][k], acc[ai][bj][m][n], 0, 0, 0); __builtin_amdgcn_s_setprio(0); } while (0)
; #define PG8_WAIT_V(n) asm volatile("s_waitcnt vmcnt(" #n ")" ::: "memory")
; #define PG8_WAIT_L(n) asm volatile("s_waitcnt lgkmcnt(" #n ")" ::: "memory")
; #define PG8_BAR __builtin_amdgcn_s_barrier()
; #define PG8_SCHED __builtin_amdgcn_sched_barrier(0)
; template <class Epi, class Sched, bool ALIGN_EPI = false, bool SP2 = false>
; __device__ __forceinline__ void gemm_phase(PG8_LAS unsigned char* lds, const Gemm g, const Sched& S, const Epi& E) {
;     ...
;         for (int t = 0; t < nt; t += 2) {
;             const bool last = (t == nt - 2);
;             const char* a1 = cA + (size_t)(t + 1) * kstep;
;             const char* a2 = last ? nA : cA + (size_t)(t + 2) * kstep; const char* b2 = last ? nB : cB + (size_t)(t + 2) * kstep;
;             const char* a3 = a2 + kstep; const char* b3 = b2 + kstep;
;             if (last && has_next) S.a_ready(nxt);
;             if constexpr (SP2) {
;             PG8_LDB(B0, 0, 0); PG8_LDB(B1, 0, 1); PG8_SCHED; PG8_LDA(At, 0, 0); PG8_STAGE(PG8_SA(1, 1), a1 + hstep, voffA);
;             PG8_WAIT_V(8); PG8_WAIT_L(0); PG8_BAR; PG8_MMA(0, 0, At, B0); PG8_MMA(0, 1, At, B1); PG8_BAR; PG8_SCHED;
.Lrot_432:
	v_add_u32_e32 v142, s56, v201
	v_add_u32_e32 v146, s58, v201
	ds_read_b128 v[130:133], v142
	ds_read_b128 v[134:137], v142 offset:1024
	ds_read_b128 v[138:141], v142 offset:2048
	ds_read_b128 v[142:145], v142 offset:3072
	ds_read_b128 v[164:167], v146
	ds_read_b128 v[168:171], v146 offset:1024
	ds_read_b128 v[172:175], v146 offset:2048
	ds_read_b128 v[176:179], v146 offset:3072
	v_lshl_add_u64 v[146:147], s[16:17], 0, v[160:161]
	s_add_i32 m0, s25, 0xc000
	ds_read_b128 v[204:207], v203
	ds_read_b128 v[208:211], v203 offset:1024
	ds_read_b128 v[212:215], v203 offset:2048
	ds_read_b128 v[216:219], v203 offset:3072
	ds_read_b128 v[220:223], v203 offset:4096
	ds_read_b128 v[224:227], v203 offset:5120
	ds_read_b128 v[228:231], v203 offset:6144
	ds_read_b128 v[232:235], v203 offset:7168
	global_load_lds_dwordx4 v[146:147], off
	v_lshl_add_u64 v[146:147], s[16:17], 0, v[162:163]
	s_add_i32 m0, s25, 0xe000
	s_nop 0
	global_load_lds_dwordx4 v[146:147], off
	s_waitcnt vmcnt(8)
	s_waitcnt lgkmcnt(0)
	s_barrier
	s_setprio 1
	s_waitcnt lgkmcnt(0)
	v_mfma_f32_16x16x32_bf16 v[126:129], v[130:133], v[204:207], v[126:129]
	v_mfma_f32_16x16x32_bf16 v[122:125], v[138:141], v[204:207], v[122:125]
	v_mfma_f32_16x16x32_bf16 v[118:121], v[130:133], v[212:215], v[118:121]
	v_mfma_f32_16x16x32_bf16 v[114:117], v[138:141], v[212:215], v[114:117]
	v_mfma_f32_16x16x32_bf16 v[110:113], v[130:133], v[220:223], v[110:113]
	v_mfma_f32_16x16x32_bf16 v[106:109], v[138:141], v[220:223], v[106:109]
	v_mfma_f32_16x16x32_bf16 v[102:105], v[130:133], v[228:231], v[102:105]
	v_mfma_f32_16x16x32_bf16 v[98:101], v[138:141], v[228:231], v[98:101]
	v_mfma_f32_16x16x32_bf16 v[126:129], v[134:137], v[208:211], v[126:129]
	v_mfma_f32_16x16x32_bf16 v[122:125], v[142:145], v[208:211], v[122:125]
	v_mfma_f32_16x16x32_bf16 v[118:121], v[134:137], v[216:219], v[118:121]
	v_mfma_f32_16x16x32_bf16 v[114:117], v[142:145], v[216:219], v[114:117]
	v_mfma_f32_16x16x32_bf16 v[110:113], v[134:137], v[224:227], v[110:113]
	v_mfma_f32_16x16x32_bf16 v[106:109], v[142:145], v[224:227], v[106:109]
	v_mfma_f32_16x16x32_bf16 v[102:105], v[134:137], v[232:235], v[102:105]
	v_mfma_f32_16x16x32_bf16 v[98:101], v[142:145], v[232:235], v[98:101]
	s_setprio 0
	s_setprio 1
	v_mfma_f32_16x16x32_bf16 v[62:65], v[164:167], v[204:207], v[62:65]
	v_mfma_f32_16x16x32_bf16 v[58:61], v[172:175], v[204:207], v[58:61]
	v_mfma_f32_16x16x32_bf16 v[54:57], v[164:167], v[212:215], v[54:57]
	v_mfma_f32_16x16x32_bf16 v[50:53], v[172:175], v[212:215], v[50:53]
	v_mfma_f32_16x16x32_bf16 v[46:49], v[164:167], v[220:223], v[46:49]
	v_mfma_f32_16x16x32_bf16 v[42:45], v[172:175], v[220:223], v[42:45]
	v_mfma_f32_16x16x32_bf16 v[38:41], v[164:167], v[228:231], v[38:41]
	v_mfma_f32_16x16x32_bf16 v[34:37], v[172:175], v[228:231], v[34:37]
	v_mfma_f32_16x16x32_bf16 v[62:65], v[168:171], v[208:211], v[62:65]
	v_mfma_f32_16x16x32_bf16 v[58:61], v[176:179], v[208:211], v[58:61]
	v_mfma_f32_16x16x32_bf16 v[54:57], v[168:171], v[216:219], v[54:57]
	v_mfma_f32_16x16x32_bf16 v[50:53], v[176:179], v[216:219], v[50:53]
	v_mfma_f32_16x16x32_bf16 v[46:49], v[168:171], v[224:227], v[46:49]
	v_mfma_f32_16x16x32_bf16 v[42:45], v[176:179], v[224:227], v[42:45]
	v_mfma_f32_16x16x32_bf16 v[38:41], v[168:171], v[232:235], v[38:41]
	v_mfma_f32_16x16x32_bf16 v[34:37], v[176:179], v[232:235], v[34:37]
	s_setprio 0
	s_barrier
	s_add_i32 s56, s56, s24
	v_lshl_add_u64 v[146:147], s[18:19], 0, v[0:1]
	s_mov_b32 m0, s56
	ds_read_b128 v[204:207], v203 offset:16384
	ds_read_b128 v[208:211], v203 offset:17408
	ds_read_b128 v[212:215], v203 offset:18432
	ds_read_b128 v[216:219], v203 offset:19456
	ds_read_b128 v[220:223], v203 offset:20480
	ds_read_b128 v[224:227], v203 offset:21504
	ds_read_b128 v[228:231], v203 offset:22528
	ds_read_b128 v[232:235], v203 offset:23552
	global_load_lds_dwordx4 v[146:147], off
	s_add_i32 m0, s56, 0x2000
	s_add_u32 s56, s18, 0x100000
	v_lshl_add_u64 v[148:149], s[18:19], 0, v[154:155]
	s_addc_u32 s57, s19, 0
	s_add_i32 s58, s58, s24
	global_load_lds_dwordx4 v[148:149], off
	v_lshl_add_u64 v[180:181], s[56:57], 0, v[0:1]
	s_mov_b32 m0, s58
	v_lshl_add_u64 v[236:237], s[20:21], 0, v[156:157]
	global_load_lds_dwordx4 v[180:181], off
	v_lshl_add_u64 v[180:181], s[56:57], 0, v[154:155]
	s_add_i32 m0, s58, 0x2000
	s_nop 0
	global_load_lds_dwordx4 v[180:181], off
	v_lshl_add_u64 v[180:181], s[20:21], 0, v[158:159]
	s_mov_b32 m0, s25
	s_nop 0
	global_load_lds_dwordx4 v[180:181], off
	s_mov_b32 m0, s26
	s_nop 0
	global_load_lds_dwordx4 v[236:237], off
	s_waitcnt vmcnt(8)
	s_waitcnt lgkmcnt(0)
	s_barrier
; #define PG8_STAGE(bufoff, gbase, voff) do { _Pragma("unroll") for (int _i = 0; _i < 2; ++_i) \
;         __builtin_amdgcn_global_load_lds((const unsigned*)((const char*)(gbase) + (voff)[_i]), (PG8_LAS unsigned*)(lds + (bufoff) + ldsw + _i * 8192), 16, 0, 0); } while (0)
; #define PG8_LDA(dst, b, h) do { _Pragma("unroll") for (int m = 0; m < 4; ++m) _Pragma("unroll") for (int k = 0; k < 2; ++k) dst[m][k] = *(const PG8_LAS bf16x8*)(lds + PG8_SA(b, h) + aoff + m * 2048 + k * 1024); } while (0)
; #define PG8_LDB(dst, b, h) do { _Pragma("unroll") for (int n = 0; n < 2; ++n) _Pragma("unroll") for (int k = 0; k < 2; ++k) dst[n][k] = *(const PG8_LAS bf16x8*)(lds + PG8_SB(b, h) + boff + n * 2048 + k * 1024); } while (0)
; #define PG8_MMA(ai, bj, At, Bt) do { __builtin_amdgcn_s_setprio(1); _Pragma("unroll") for (int m = 0; m < 4; ++m) _Pragma("unroll") for (int n = 0; n < 2; ++n) _Pragma("unroll") for (int k = 0; k < 2; ++k) \
;         acc[ai][bj][m][n] = __builtin_amdgcn_mfma_f32_16x16x32_bf16(Bt[n][k], At[m][k], acc[ai][bj][m][n], 0, 0, 0); __builtin_amdgcn_s_setprio(0); } while (0)
; #define PG8_WAIT_V(n) asm volatile("s_waitcnt vmcnt(" #n ")" ::: "memory")
; #define PG8_WAIT_L(n) asm volatile("s_waitcnt lgkmcnt(" #n ")" ::: "memory")
; #define PG8_BAR __builtin_amdgcn_s_barrier()
; #define PG8_SCHED __builtin_amdgcn_sched_barrier(0)
; template <class Epi, class Sched, bool ALIGN_EPI = false, bool SP2 = false>
; __device__ __forceinline__ void gemm_phase(PG8_LAS unsigned char* lds, const Gemm g, const Sched& S, const Epi& E) {
;     ...
;             PG8_WAIT_V(8); PG8_WAIT_L(0); PG8_BAR; PG8_MMA(0, 0, At, B0); PG8_MMA(0, 1, At, B1); PG8_BAR; PG8_SCHED;
;             PG8_LDA(At, 0, 1); PG8_STAGE(PG8_SB(0, 0), b2, voffB); PG8_STAGE(PG8_SB(0, 1), b2 + hstep, voffB); PG8_STAGE(PG8_SA(0, 0), a2, voffA);
;             PG8_WAIT_V(8); PG8_WAIT_L(0); PG8_BAR; PG8_MMA(1, 0, At, B0); PG8_MMA(1, 1, At, B1); PG8_BAR; PG8_SCHED;
;             PG8_LDB(B0, 1, 0); PG8_LDB(B1, 1, 1); PG8_SCHED; PG8_LDA(At, 1, 0); PG8_STAGE(PG8_SA(0, 1), a2 + hstep, voffA);
;             PG8_WAIT_V(8); PG8_WAIT_L(0); PG8_BAR; PG8_MMA(0, 0, At, B0); PG8_MMA(0, 1, At, B1); PG8_BAR; PG8_SCHED;
	s_setprio 1
	s_waitcnt lgkmcnt(0)
	v_mfma_f32_16x16x32_bf16 v[94:97], v[130:133], v[204:207], v[94:97]
	v_mfma_f32_16x16x32_bf16 v[90:93], v[138:141], v[204:207], v[90:93]
	v_mfma_f32_16x16x32_bf16 v[86:89], v[130:133], v[212:215], v[86:89]
	v_mfma_f32_16x16x32_bf16 v[82:85], v[138:141], v[212:215], v[82:85]
	v_mfma_f32_16x16x32_bf16 v[78:81], v[130:133], v[220:223], v[78:81]
	v_mfma_f32_16x16x32_bf16 v[74:77], v[138:141], v[220:223], v[74:77]
	v_mfma_f32_16x16x32_bf16 v[70:73], v[130:133], v[228:231], v[70:73]
	v_mfma_f32_16x16x32_bf16 v[66:69], v[138:141], v[228:231], v[66:69]
	v_mfma_f32_16x16x32_bf16 v[94:97], v[134:137], v[208:211], v[94:97]
	v_mfma_f32_16x16x32_bf16 v[90:93], v[142:145], v[208:211], v[90:93]
	v_mfma_f32_16x16x32_bf16 v[86:89], v[134:137], v[216:219], v[86:89]
	v_mfma_f32_16x16x32_bf16 v[82:85], v[142:145], v[216:219], v[82:85]
	v_mfma_f32_16x16x32_bf16 v[78:81], v[134:137], v[224:227], v[78:81]
	v_mfma_f32_16x16x32_bf16 v[74:77], v[142:145], v[224:227], v[74:77]
	v_mfma_f32_16x16x32_bf16 v[70:73], v[134:137], v[232:235], v[70:73]
	v_mfma_f32_16x16x32_bf16 v[66:69], v[142:145], v[232:235], v[66:69]
	s_setprio 0
	s_setprio 1
	v_mfma_f32_16x16x32_bf16 v[30:33], v[164:167], v[204:207], v[30:33]
	v_mfma_f32_16x16x32_bf16 v[26:29], v[172:175], v[204:207], v[26:29]
	v_mfma_f32_16x16x32_bf16 v[22:25], v[164:167], v[212:215], v[22:25]
	v_mfma_f32_16x16x32_bf16 v[18:21], v[172:175], v[212:215], v[18:21]
	v_mfma_f32_16x16x32_bf16 v[14:17], v[164:167], v[220:223], v[14:17]
	v_mfma_f32_16x16x32_bf16 v[10:13], v[172:175], v[220:223], v[10:13]
	v_mfma_f32_16x16x32_bf16 v[6:9], v[164:167], v[228:231], v[6:9]
	v_mfma_f32_16x16x32_bf16 v[2:5], v[172:175], v[228:231], v[2:5]
	v_mfma_f32_16x16x32_bf16 v[30:33], v[168:171], v[208:211], v[30:33]
	v_mfma_f32_16x16x32_bf16 v[26:29], v[176:179], v[208:211], v[26:29]
	v_mfma_f32_16x16x32_bf16 v[22:25], v[168:171], v[216:219], v[22:25]
	v_mfma_f32_16x16x32_bf16 v[18:21], v[176:179], v[216:219], v[18:21]
	v_mfma_f32_16x16x32_bf16 v[14:17], v[168:171], v[224:227], v[14:17]
	v_mfma_f32_16x16x32_bf16 v[10:13], v[176:179], v[224:227], v[10:13]
	v_mfma_f32_16x16x32_bf16 v[6:9], v[168:171], v[232:235], v[6:9]
	v_mfma_f32_16x16x32_bf16 v[2:5], v[176:179], v[232:235], v[2:5]
	s_setprio 0
	s_barrier
	s_add_i32 s56, 0, 0x18000
	s_add_i32 s57, 0, 0x1c000
	v_add_u32_e32 v142, s56, v201
	v_add_u32_e32 v176, s57, v201
	ds_read_b128 v[130:133], v142
	ds_read_b128 v[134:137], v142 offset:1024
	ds_read_b128 v[138:141], v142 offset:2048
	ds_read_b128 v[142:145], v142 offset:3072
	ds_read_b128 v[164:167], v176
	ds_read_b128 v[168:171], v176 offset:1024
	ds_read_b128 v[172:175], v176 offset:2048
	ds_read_b128 v[176:179], v176 offset:3072
	s_add_u32 s20, s20, 0x100000
	s_addc_u32 s21, s21, 0
	s_mov_b32 m0, s27
	v_lshl_add_u64 v[238:239], s[20:21], 0, v[158:159]
	ds_read_b128 v[204:207], v203 offset:32768
	ds_read_b128 v[208:211], v203 offset:33792
	ds_read_b128 v[212:215], v203 offset:34816
	ds_read_b128 v[216:219], v203 offset:35840
	ds_read_b128 v[220:223], v203 offset:36864
	ds_read_b128 v[224:227], v203 offset:37888
	ds_read_b128 v[228:231], v203 offset:38912
	ds_read_b128 v[232:235], v203 offset:39936
	global_load_lds_dwordx4 v[238:239], off
	v_lshl_add_u64 v[238:239], s[20:21], 0, v[156:157]
	s_mov_b32 m0, s28
	s_nop 0
	global_load_lds_dwordx4 v[238:239], off
	s_waitcnt vmcnt(8)
	s_waitcnt lgkmcnt(0)
	s_barrier
	s_setprio 1
	s_waitcnt lgkmcnt(0)
	v_mfma_f32_16x16x32_bf16 v[126:129], v[130:133], v[204:207], v[126:129]
	v_mfma_f32_16x16x32_bf16 v[122:125], v[138:141], v[204:207], v[122:125]
	v_mfma_f32_16x16x32_bf16 v[118:121], v[130:133], v[212:215], v[118:121]
	v_mfma_f32_16x16x32_bf16 v[114:117], v[138:141], v[212:215], v[114:117]
	v_mfma_f32_16x16x32_bf16 v[110:113], v[130:133], v[220:223], v[110:113]
	v_mfma_f32_16x16x32_bf16 v[106:109], v[138:141], v[220:223], v[106:109]
	v_mfma_f32_16x16x32_bf16 v[102:105], v[130:133], v[228:231], v[102:105]
	v_mfma_f32_16x16x32_bf16 v[98:101], v[138:141], v[228:231], v[98:101]
	v_mfma_f32_16x16x32_bf16 v[126:129], v[134:137], v[208:211], v[126:129]
	v_mfma_f32_16x16x32_bf16 v[122:125], v[142:145], v[208:211], v[122:125]
	v_mfma_f32_16x16x32_bf16 v[118:121], v[134:137], v[216:219], v[118:121]
	v_mfma_f32_16x16x32_bf16 v[114:117], v[142:145], v[216:219], v[114:117]
	v_mfma_f32_16x16x32_bf16 v[110:113], v[134:137], v[224:227], v[110:113]
	v_mfma_f32_16x16x32_bf16 v[106:109], v[142:145], v[224:227], v[106:109]
	v_mfma_f32_16x16x32_bf16 v[102:105], v[134:137], v[232:235], v[102:105]
	v_mfma_f32_16x16x32_bf16 v[98:101], v[142:145], v[232:235], v[98:101]
	s_setprio 0
	s_setprio 1
	v_mfma_f32_16x16x32_bf16 v[62:65], v[164:167], v[204:207], v[62:65]
	v_mfma_f32_16x16x32_bf16 v[58:61], v[172:175], v[204:207], v[58:61]
	v_mfma_f32_16x16x32_bf16 v[54:57], v[164:167], v[212:215], v[54:57]
	v_mfma_f32_16x16x32_bf16 v[50:53], v[172:175], v[212:215], v[50:53]
	v_mfma_f32_16x16x32_bf16 v[46:49], v[164:167], v[220:223], v[46:49]
	v_mfma_f32_16x16x32_bf16 v[42:45], v[172:175], v[220:223], v[42:45]
	v_mfma_f32_16x16x32_bf16 v[38:41], v[164:167], v[228:231], v[38:41]
	v_mfma_f32_16x16x32_bf16 v[34:37], v[172:175], v[228:231], v[34:37]
	v_mfma_f32_16x16x32_bf16 v[62:65], v[168:171], v[208:211], v[62:65]
	v_mfma_f32_16x16x32_bf16 v[58:61], v[176:179], v[208:211], v[58:61]
	v_mfma_f32_16x16x32_bf16 v[54:57], v[168:171], v[216:219], v[54:57]
	v_mfma_f32_16x16x32_bf16 v[50:53], v[176:179], v[216:219], v[50:53]
	v_mfma_f32_16x16x32_bf16 v[46:49], v[168:171], v[224:227], v[46:49]
	v_mfma_f32_16x16x32_bf16 v[42:45], v[176:179], v[224:227], v[42:45]
	v_mfma_f32_16x16x32_bf16 v[38:41], v[168:171], v[232:235], v[38:41]
	v_mfma_f32_16x16x32_bf16 v[34:37], v[176:179], v[232:235], v[34:37]
	s_setprio 0
	s_barrier
; #define PG8_STAGE(bufoff, gbase, voff) do { _Pragma("unroll") for (int _i = 0; _i < 2; ++_i) \
;         __builtin_amdgcn_global_load_lds((const unsigned*)((const char*)(gbase) + (voff)[_i]), (PG8_LAS unsigned*)(lds + (bufoff) + ldsw + _i * 8192), 16, 0, 0); } while (0)
; #define PG8_LDA(dst, b, h) do { _Pragma("unroll") for (int m = 0; m < 4; ++m) _Pragma("unroll") for (int k = 0; k < 2; ++k) dst[m][k] = *(const PG8_LAS bf16x8*)(lds + PG8_SA(b, h) + aoff + m * 2048 + k * 1024); } while (0)
; #define PG8_MMA(ai, bj, At, Bt) do { __builtin_amdgcn_s_setprio(1); _Pragma("unroll") for (int m = 0; m < 4; ++m) _Pragma("unroll") for (int n = 0; n < 2; ++n) _Pragma("unroll") for (int k = 0; k < 2; ++k) \
;         acc[ai][bj][m][n] = __builtin_amdgcn_mfma_f32_16x16x32_bf16(Bt[n][k], At[m][k], acc[ai][bj][m][n], 0, 0, 0); __builtin_amdgcn_s_setprio(0); } while (0)
; #define PG8_WAIT_V(n) asm volatile("s_waitcnt vmcnt(" #n ")" ::: "memory")
; #define PG8_WAIT_L(n) asm volatile("s_waitcnt lgkmcnt(" #n ")" ::: "memory")
; #define PG8_BAR __builtin_amdgcn_s_barrier()
; #define PG8_SCHED __builtin_amdgcn_sched_barrier(0)
; template <class Epi, class Sched, bool ALIGN_EPI = false, bool SP2 = false>
; __device__ __forceinline__ void gemm_phase(PG8_LAS unsigned char* lds, const Gemm g, const Sched& S, const Epi& E) {
;     ...
;         for (int t = 0; t < nt; t += 2) {
;             const bool last = (t == nt - 2);
;             const char* a1 = cA + (size_t)(t + 1) * kstep;
;             const char* a2 = last ? nA : cA + (size_t)(t + 2) * kstep; const char* b2 = last ? nB : cB + (size_t)(t + 2) * kstep;
;             const char* a3 = a2 + kstep; const char* b3 = b2 + kstep;
;             if (last && has_next) S.a_ready(nxt);
;     ...
;             PG8_WAIT_V(8); PG8_WAIT_L(0); PG8_BAR; PG8_MMA(0, 0, At, B0); PG8_MMA(0, 1, At, B1); PG8_BAR; PG8_SCHED;
;             PG8_LDA(At, 1, 1); PG8_STAGE(PG8_SB(1, 0), b3, voffB); PG8_STAGE(PG8_SB(1, 1), b3 + hstep, voffB); PG8_STAGE(PG8_SA(1, 0), a3, voffA);
;             PG8_WAIT_V(8); PG8_WAIT_L(0); PG8_BAR; PG8_MMA(1, 0, At, B0); PG8_MMA(1, 1, At, B1); PG8_BAR; PG8_SCHED;
	s_add_i32 s20, s56, s24
	v_lshl_add_u64 v[146:147], v[146:147], 0, s[38:39]
	s_mov_b32 m0, s20
	ds_read_b128 v[204:207], v203 offset:49152
	ds_read_b128 v[208:211], v203 offset:50176
	ds_read_b128 v[212:215], v203 offset:51200
	ds_read_b128 v[216:219], v203 offset:52224
	ds_read_b128 v[220:223], v203 offset:53248
	ds_read_b128 v[224:227], v203 offset:54272
	ds_read_b128 v[228:231], v203 offset:55296
	ds_read_b128 v[232:235], v203 offset:56320
	global_load_lds_dwordx4 v[146:147], off
	s_add_i32 m0, s20, 0x2000
	s_add_u32 s18, s18, 0x100080
	v_lshl_add_u64 v[146:147], v[148:149], 0, s[38:39]
	s_addc_u32 s19, s19, 0
	s_add_i32 s20, s57, s24
	global_load_lds_dwordx4 v[146:147], off
	v_lshl_add_u64 v[146:147], s[18:19], 0, v[0:1]
	s_mov_b32 m0, s20
	s_nop 0
	global_load_lds_dwordx4 v[146:147], off
	v_lshl_add_u64 v[146:147], s[18:19], 0, v[154:155]
	s_add_i32 m0, s20, 0x2000
	s_nop 0
	global_load_lds_dwordx4 v[146:147], off
	v_lshl_add_u64 v[146:147], v[180:181], 0, s[38:39]
	s_mov_b32 m0, s31
	s_nop 0
	global_load_lds_dwordx4 v[146:147], off
	v_lshl_add_u64 v[146:147], v[236:237], 0, s[38:39]
	s_mov_b32 m0, s33
	s_nop 0
	global_load_lds_dwordx4 v[146:147], off
	s_waitcnt vmcnt(8)
	s_waitcnt lgkmcnt(0)
	s_barrier
	s_setprio 1
	s_waitcnt lgkmcnt(0)
	v_mfma_f32_16x16x32_bf16 v[94:97], v[130:133], v[204:207], v[94:97]
	v_mfma_f32_16x16x32_bf16 v[90:93], v[138:141], v[204:207], v[90:93]
	v_mfma_f32_16x16x32_bf16 v[86:89], v[130:133], v[212:215], v[86:89]
	v_mfma_f32_16x16x32_bf16 v[82:85], v[138:141], v[212:215], v[82:85]
	v_mfma_f32_16x16x32_bf16 v[78:81], v[130:133], v[220:223], v[78:81]
	v_mfma_f32_16x16x32_bf16 v[74:77], v[138:141], v[220:223], v[74:77]
	v_mfma_f32_16x16x32_bf16 v[70:73], v[130:133], v[228:231], v[70:73]
	v_mfma_f32_16x16x32_bf16 v[66:69], v[138:141], v[228:231], v[66:69]
	v_mfma_f32_16x16x32_bf16 v[94:97], v[134:137], v[208:211], v[94:97]
	v_mfma_f32_16x16x32_bf16 v[90:93], v[142:145], v[208:211], v[90:93]
	v_mfma_f32_16x16x32_bf16 v[86:89], v[134:137], v[216:219], v[86:89]
	v_mfma_f32_16x16x32_bf16 v[82:85], v[142:145], v[216:219], v[82:85]
	v_mfma_f32_16x16x32_bf16 v[78:81], v[134:137], v[224:227], v[78:81]
	v_mfma_f32_16x16x32_bf16 v[74:77], v[142:145], v[224:227], v[74:77]
	v_mfma_f32_16x16x32_bf16 v[70:73], v[134:137], v[232:235], v[70:73]
	v_mfma_f32_16x16x32_bf16 v[66:69], v[142:145], v[232:235], v[66:69]
	s_setprio 0
	s_setprio 1
	v_mfma_f32_16x16x32_bf16 v[30:33], v[164:167], v[204:207], v[30:33]
	v_mfma_f32_16x16x32_bf16 v[26:29], v[172:175], v[204:207], v[26:29]
	v_mfma_f32_16x16x32_bf16 v[22:25], v[164:167], v[212:215], v[22:25]
	v_mfma_f32_16x16x32_bf16 v[18:21], v[172:175], v[212:215], v[18:21]
	v_mfma_f32_16x16x32_bf16 v[14:17], v[164:167], v[220:223], v[14:17]
	v_mfma_f32_16x16x32_bf16 v[10:13], v[172:175], v[220:223], v[10:13]
	v_mfma_f32_16x16x32_bf16 v[6:9], v[164:167], v[228:231], v[6:9]
	v_mfma_f32_16x16x32_bf16 v[2:5], v[172:175], v[228:231], v[2:5]
	v_mfma_f32_16x16x32_bf16 v[30:33], v[168:171], v[208:211], v[30:33]
	v_mfma_f32_16x16x32_bf16 v[26:29], v[176:179], v[208:211], v[26:29]
	v_mfma_f32_16x16x32_bf16 v[22:25], v[168:171], v[216:219], v[22:25]
	v_mfma_f32_16x16x32_bf16 v[18:21], v[176:179], v[216:219], v[18:21]
	v_mfma_f32_16x16x32_bf16 v[14:17], v[168:171], v[224:227], v[14:17]
	v_mfma_f32_16x16x32_bf16 v[10:13], v[176:179], v[224:227], v[10:13]
	v_mfma_f32_16x16x32_bf16 v[6:9], v[168:171], v[232:235], v[6:9]
	v_mfma_f32_16x16x32_bf16 v[2:5], v[176:179], v[232:235], v[2:5]
	s_setprio 0
	s_add_i32 s55, s55, 2
	s_add_u32 s16, s16, 0x100
	s_addc_u32 s17, s17, 0
	s_add_u32 s53, s53, 0x100
	s_addc_u32 s54, s54, 0
	s_add_u32 s18, s16, 0xfff00080
	s_addc_u32 s19, s17, -1
	s_add_i32 s56, 0, 0x10000
	s_cmp_eq_u32 s55, 60
	s_cselect_b32 s21, s11, s19
	s_cselect_b32 s20, s51, s18
	s_cselect_b32 s19, s9, s54
	s_cselect_b32 s18, s52, s53
	s_add_i32 s58, 0, 0x14000
	s_barrier
	s_cmp_gt_u32 s55, 61
	s_cbranch_scc0 .Lrot_432
	s_and_b64 vcc, exec, s[6:7]
	s_cbranch_vccz .LBB0_435
	s_barrier

; #define PG8_STAGE(bufoff, gbase, voff) do { _Pragma("unroll") for (int _i = 0; _i < 2; ++_i) \
;         __builtin_amdgcn_global_load_lds((const unsigned*)((const char*)(gbase) + (voff)[_i]), (PG8_LAS unsigned*)(lds + (bufoff) + ldsw + _i * 8192), 16, 0, 0); } while (0)
; #define PG8_LDA(dst, b, h) do { _Pragma("unroll") for (int m = 0; m < 4; ++m) _Pragma("unroll") for (int k = 0; k < 2; ++k) dst[m][k] = *(const PG8_LAS bf16x8*)(lds + PG8_SA(b, h) + aoff + m * 2048 + k * 1024); } while (0)
; #define PG8_LDB(dst, b, h) do { _Pragma("unroll") for (int n = 0; n < 2; ++n) _Pragma("unroll") for (int k = 0; k < 2; ++k) dst[n][k] = *(const PG8_LAS bf16x8*)(lds + PG8_SB(b, h) + boff + n * 2048 + k * 1024); } while (0)
; #define PG8_MMA(ai, bj, At, Bt) do { __builtin_amdgcn_s_setprio(1); _Pragma("unroll") for (int m = 0; m < 4; ++m) _Pragma("unroll") for (int n = 0; n < 2; ++n) _Pragma("unroll") for (int k = 0; k < 2; ++k) \
;         acc[ai][bj][m][n] = __builtin_amdgcn_mfma_f32_16x16x32_bf16(Bt[n][k], At[m][k], acc[ai][bj][m][n], 0, 0, 0); __builtin_amdgcn_s_setprio(0); } while (0)
; #define PG8_WAIT_V(n) asm volatile("s_waitcnt vmcnt(" #n ")" ::: "memory")
; #define PG8_WAIT_L(n) asm volatile("s_waitcnt lgkmcnt(" #n ")" ::: "memory")
; #define PG8_BAR __builtin_amdgcn_s_barrier()
; #define PG8_SCHED __builtin_amdgcn_sched_barrier(0)
; template <class Epi, class Sched, bool ALIGN_EPI = false, bool SP2 = false>
; __device__ __forceinline__ void gemm_phase(PG8_LAS unsigned char* lds, const Gemm g, const Sched& S, const Epi& E) {
;     ...
;         for (int t = 0; t < nt; t += 2) {
;             const bool last = (t == nt - 2);
;             const char* a1 = cA + (size_t)(t + 1) * kstep;
;             const char* a2 = last ? nA : cA + (size_t)(t + 2) * kstep; const char* b2 = last ? nB : cB + (size_t)(t + 2) * kstep;
;             const char* a3 = a2 + kstep; const char* b3 = b2 + kstep;
;             if (last && has_next) S.a_ready(nxt);
;             if constexpr (SP2) {
;             PG8_LDB(B0, 0, 0); PG8_LDB(B1, 0, 1); PG8_SCHED; PG8_LDA(At, 0, 0); PG8_STAGE(PG8_SA(1, 1), a1 + hstep, voffA);
;             PG8_WAIT_V(8); PG8_WAIT_L(0); PG8_BAR; PG8_MMA(0, 0, At, B0); PG8_MMA(0, 1, At, B1); PG8_BAR; PG8_SCHED;
.LBB0_558:
	s_add_u32 s24, s22, 0xfffc0080
	s_addc_u32 s25, s23, -1
	s_add_i32 s64, 0, 0x10000
	s_cmp_eq_u32 s63, 12
	s_cselect_b32 s27, s15, s25
	s_cselect_b32 s26, s21, s24
	s_cselect_b32 s25, s13, s62
	s_cselect_b32 s24, s60, s61
	s_add_i32 s66, 0, 0x14000
.Lrot_558:
	v_add_u32_e32 v0, s64, v175
	ds_read_b128 v[130:133], v0
	ds_read_b128 v[134:137], v0 offset:1024
	ds_read_b128 v[138:141], v0 offset:2048
	ds_read_b128 v[142:145], v0 offset:3072
	v_add_u32_e32 v0, s66, v175
	ds_read_b128 v[168:171], v0
	ds_read_b128 v[200:203], v0 offset:1024
	ds_read_b128 v[204:207], v0 offset:2048
	ds_read_b128 v[208:211], v0 offset:3072
	v_lshl_add_u64 v[146:147], s[22:23], 0, v[164:165]
	s_add_i32 m0, s50, 0xc000
	ds_read_b128 v[212:215], v177
	ds_read_b128 v[216:219], v177 offset:1024
	ds_read_b128 v[220:223], v177 offset:2048
	ds_read_b128 v[224:227], v177 offset:3072
	ds_read_b128 v[228:231], v177 offset:4096
	ds_read_b128 v[232:235], v177 offset:5120
	ds_read_b128 v[236:239], v177 offset:6144
	ds_read_b128 v[240:243], v177 offset:7168
	global_load_lds_dwordx4 v[146:147], off
	v_lshl_add_u64 v[146:147], s[22:23], 0, v[166:167]
	s_add_i32 m0, s50, 0xe000
	s_nop 0
	global_load_lds_dwordx4 v[146:147], off
	s_waitcnt vmcnt(8)
	s_waitcnt lgkmcnt(0)
	s_barrier
	s_setprio 1
	s_waitcnt lgkmcnt(0)
	v_mfma_f32_16x16x32_bf16 v[126:129], v[130:133], v[212:215], v[126:129]
	v_mfma_f32_16x16x32_bf16 v[122:125], v[138:141], v[212:215], v[122:125]
	v_mfma_f32_16x16x32_bf16 v[114:117], v[130:133], v[220:223], v[114:117]
	v_mfma_f32_16x16x32_bf16 v[106:109], v[138:141], v[220:223], v[106:109]
	v_mfma_f32_16x16x32_bf16 v[94:97], v[130:133], v[228:231], v[94:97]
	v_mfma_f32_16x16x32_bf16 v[90:93], v[138:141], v[228:231], v[90:93]
	v_mfma_f32_16x16x32_bf16 v[82:85], v[130:133], v[236:239], v[82:85]
	v_mfma_f32_16x16x32_bf16 v[74:77], v[138:141], v[236:239], v[74:77]
	v_mfma_f32_16x16x32_bf16 v[126:129], v[134:137], v[216:219], v[126:129]
	v_mfma_f32_16x16x32_bf16 v[122:125], v[142:145], v[216:219], v[122:125]
	v_mfma_f32_16x16x32_bf16 v[114:117], v[134:137], v[224:227], v[114:117]
	v_mfma_f32_16x16x32_bf16 v[106:109], v[142:145], v[224:227], v[106:109]
	v_mfma_f32_16x16x32_bf16 v[94:97], v[134:137], v[232:235], v[94:97]
	v_mfma_f32_16x16x32_bf16 v[90:93], v[142:145], v[232:235], v[90:93]
	v_mfma_f32_16x16x32_bf16 v[82:85], v[134:137], v[240:243], v[82:85]
	v_mfma_f32_16x16x32_bf16 v[74:77], v[142:145], v[240:243], v[74:77]
	s_setprio 0
	s_setprio 1
	v_mfma_f32_16x16x32_bf16 v[118:121], v[168:171], v[212:215], v[118:121]
	v_mfma_f32_16x16x32_bf16 v[110:113], v[204:207], v[212:215], v[110:113]
	v_mfma_f32_16x16x32_bf16 v[102:105], v[168:171], v[220:223], v[102:105]
	v_mfma_f32_16x16x32_bf16 v[98:101], v[204:207], v[220:223], v[98:101]
	v_mfma_f32_16x16x32_bf16 v[86:89], v[168:171], v[228:231], v[86:89]
	v_mfma_f32_16x16x32_bf16 v[78:81], v[204:207], v[228:231], v[78:81]
	v_mfma_f32_16x16x32_bf16 v[70:73], v[168:171], v[236:239], v[70:73]
	v_mfma_f32_16x16x32_bf16 v[66:69], v[204:207], v[236:239], v[66:69]
	v_mfma_f32_16x16x32_bf16 v[118:121], v[200:203], v[216:219], v[118:121]
	v_mfma_f32_16x16x32_bf16 v[110:113], v[208:211], v[216:219], v[110:113]
	v_mfma_f32_16x16x32_bf16 v[102:105], v[200:203], v[224:227], v[102:105]
	v_mfma_f32_16x16x32_bf16 v[98:101], v[208:211], v[224:227], v[98:101]
	v_mfma_f32_16x16x32_bf16 v[86:89], v[200:203], v[232:235], v[86:89]
	v_mfma_f32_16x16x32_bf16 v[78:81], v[208:211], v[232:235], v[78:81]
	v_mfma_f32_16x16x32_bf16 v[70:73], v[200:203], v[240:243], v[70:73]
	v_mfma_f32_16x16x32_bf16 v[66:69], v[208:211], v[240:243], v[66:69]
	s_setprio 0
	s_barrier
	s_add_i32 s64, s64, s30
	v_lshl_add_u64 v[146:147], s[24:25], 0, v[158:159]
	s_mov_b32 m0, s64
	ds_read_b128 v[212:215], v177 offset:16384
	ds_read_b128 v[216:219], v177 offset:17408
	ds_read_b128 v[220:223], v177 offset:18432
	ds_read_b128 v[224:227], v177 offset:19456
	ds_read_b128 v[228:231], v177 offset:20480
	ds_read_b128 v[232:235], v177 offset:21504
	ds_read_b128 v[236:239], v177 offset:22528
	ds_read_b128 v[240:243], v177 offset:23552
	global_load_lds_dwordx4 v[146:147], off
	s_add_i32 m0, s64, 0x2000
	s_add_u32 s64, s24, 0x40000
	v_lshl_add_u64 v[148:149], s[24:25], 0, v[154:155]
	s_addc_u32 s65, s25, 0
	s_add_i32 s66, s66, s30
	global_load_lds_dwordx4 v[148:149], off
	v_lshl_add_u64 v[172:173], s[64:65], 0, v[158:159]
	s_mov_b32 m0, s66
	v_lshl_add_u64 v[180:181], s[26:27], 0, v[156:157]
	global_load_lds_dwordx4 v[172:173], off
	v_lshl_add_u64 v[172:173], s[64:65], 0, v[154:155]
	s_add_i32 m0, s66, 0x2000
	s_nop 0
	global_load_lds_dwordx4 v[172:173], off
	v_lshl_add_u64 v[172:173], s[26:27], 0, v[160:161]
	s_mov_b32 m0, s50
	s_nop 0
	global_load_lds_dwordx4 v[172:173], off
	s_mov_b32 m0, s51
	s_nop 0
	global_load_lds_dwordx4 v[180:181], off
	s_waitcnt vmcnt(8)
	s_waitcnt lgkmcnt(0)
	s_barrier
; #define PG8_STAGE(bufoff, gbase, voff) do { _Pragma("unroll") for (int _i = 0; _i < 2; ++_i) \
;         __builtin_amdgcn_global_load_lds((const unsigned*)((const char*)(gbase) + (voff)[_i]), (PG8_LAS unsigned*)(lds + (bufoff) + ldsw + _i * 8192), 16, 0, 0); } while (0)
; #define PG8_LDA(dst, b, h) do { _Pragma("unroll") for (int m = 0; m < 4; ++m) _Pragma("unroll") for (int k = 0; k < 2; ++k) dst[m][k] = *(const PG8_LAS bf16x8*)(lds + PG8_SA(b, h) + aoff + m * 2048 + k * 1024); } while (0)
; #define PG8_LDB(dst, b, h) do { _Pragma("unroll") for (int n = 0; n < 2; ++n) _Pragma("unroll") for (int k = 0; k < 2; ++k) dst[n][k] = *(const PG8_LAS bf16x8*)(lds + PG8_SB(b, h) + boff + n * 2048 + k * 1024); } while (0)
; #define PG8_MMA(ai, bj, At, Bt) do { __builtin_amdgcn_s_setprio(1); _Pragma("unroll") for (int m = 0; m < 4; ++m) _Pragma("unroll") for (int n = 0; n < 2; ++n) _Pragma("unroll") for (int k = 0; k < 2; ++k) \
;         acc[ai][bj][m][n] = __builtin_amdgcn_mfma_f32_16x16x32_bf16(Bt[n][k], At[m][k], acc[ai][bj][m][n], 0, 0, 0); __builtin_amdgcn_s_setprio(0); } while (0)
; #define PG8_WAIT_V(n) asm volatile("s_waitcnt vmcnt(" #n ")" ::: "memory")
; #define PG8_WAIT_L(n) asm volatile("s_waitcnt lgkmcnt(" #n ")" ::: "memory")
; #define PG8_BAR __builtin_amdgcn_s_barrier()
; #define PG8_SCHED __builtin_amdgcn_sched_barrier(0)
; template <class Epi, class Sched, bool ALIGN_EPI = false, bool SP2 = false>
; __device__ __forceinline__ void gemm_phase(PG8_LAS unsigned char* lds, const Gemm g, const Sched& S, const Epi& E) {
;     ...
;             PG8_WAIT_V(8); PG8_WAIT_L(0); PG8_BAR; PG8_MMA(0, 0, At, B0); PG8_MMA(0, 1, At, B1); PG8_BAR; PG8_SCHED;
;             PG8_LDA(At, 0, 1); PG8_STAGE(PG8_SB(0, 0), b2, voffB); PG8_STAGE(PG8_SB(0, 1), b2 + hstep, voffB); PG8_STAGE(PG8_SA(0, 0), a2, voffA);
;             PG8_WAIT_V(8); PG8_WAIT_L(0); PG8_BAR; PG8_MMA(1, 0, At, B0); PG8_MMA(1, 1, At, B1); PG8_BAR; PG8_SCHED;
;             PG8_LDB(B0, 1, 0); PG8_LDB(B1, 1, 1); PG8_SCHED; PG8_LDA(At, 1, 0); PG8_STAGE(PG8_SA(0, 1), a2 + hstep, voffA);
;             PG8_WAIT_V(8); PG8_WAIT_L(0); PG8_BAR; PG8_MMA(0, 0, At, B0); PG8_MMA(0, 1, At, B1); PG8_BAR; PG8_SCHED;
	s_setprio 1
	s_waitcnt lgkmcnt(0)
	v_mfma_f32_16x16x32_bf16 v[62:65], v[130:133], v[212:215], v[62:65]
	v_mfma_f32_16x16x32_bf16 v[58:61], v[138:141], v[212:215], v[58:61]
	v_mfma_f32_16x16x32_bf16 v[50:53], v[130:133], v[220:223], v[50:53]
	v_mfma_f32_16x16x32_bf16 v[42:45], v[138:141], v[220:223], v[42:45]
	v_mfma_f32_16x16x32_bf16 v[30:33], v[130:133], v[228:231], v[30:33]
	v_mfma_f32_16x16x32_bf16 v[26:29], v[138:141], v[228:231], v[26:29]
	v_mfma_f32_16x16x32_bf16 v[18:21], v[130:133], v[236:239], v[18:21]
	v_mfma_f32_16x16x32_bf16 v[10:13], v[138:141], v[236:239], v[10:13]
	v_mfma_f32_16x16x32_bf16 v[62:65], v[134:137], v[216:219], v[62:65]
	v_mfma_f32_16x16x32_bf16 v[58:61], v[142:145], v[216:219], v[58:61]
	v_mfma_f32_16x16x32_bf16 v[50:53], v[134:137], v[224:227], v[50:53]
	v_mfma_f32_16x16x32_bf16 v[42:45], v[142:145], v[224:227], v[42:45]
	v_mfma_f32_16x16x32_bf16 v[30:33], v[134:137], v[232:235], v[30:33]
	v_mfma_f32_16x16x32_bf16 v[26:29], v[142:145], v[232:235], v[26:29]
	v_mfma_f32_16x16x32_bf16 v[18:21], v[134:137], v[240:243], v[18:21]
	v_mfma_f32_16x16x32_bf16 v[10:13], v[142:145], v[240:243], v[10:13]
	s_setprio 0
	s_setprio 1
	v_mfma_f32_16x16x32_bf16 v[54:57], v[168:171], v[212:215], v[54:57]
	v_mfma_f32_16x16x32_bf16 v[46:49], v[204:207], v[212:215], v[46:49]
	v_mfma_f32_16x16x32_bf16 v[38:41], v[168:171], v[220:223], v[38:41]
	v_mfma_f32_16x16x32_bf16 v[34:37], v[204:207], v[220:223], v[34:37]
	v_mfma_f32_16x16x32_bf16 v[22:25], v[168:171], v[228:231], v[22:25]
	v_mfma_f32_16x16x32_bf16 v[14:17], v[204:207], v[228:231], v[14:17]
	v_mfma_f32_16x16x32_bf16 v[6:9], v[168:171], v[236:239], v[6:9]
	v_mfma_f32_16x16x32_bf16 v[2:5], v[204:207], v[236:239], v[2:5]
	v_mfma_f32_16x16x32_bf16 v[54:57], v[200:203], v[216:219], v[54:57]
	v_mfma_f32_16x16x32_bf16 v[46:49], v[208:211], v[216:219], v[46:49]
	v_mfma_f32_16x16x32_bf16 v[38:41], v[200:203], v[224:227], v[38:41]
	v_mfma_f32_16x16x32_bf16 v[34:37], v[208:211], v[224:227], v[34:37]
	v_mfma_f32_16x16x32_bf16 v[22:25], v[200:203], v[232:235], v[22:25]
	v_mfma_f32_16x16x32_bf16 v[14:17], v[208:211], v[232:235], v[14:17]
	v_mfma_f32_16x16x32_bf16 v[6:9], v[200:203], v[240:243], v[6:9]
	v_mfma_f32_16x16x32_bf16 v[2:5], v[208:211], v[240:243], v[2:5]
	s_setprio 0
	s_barrier
	s_add_i32 s64, 0, 0x18000
	v_add_u32_e32 v0, s64, v175
	s_add_i32 s65, 0, 0x1c000
	ds_read_b128 v[130:133], v0
	ds_read_b128 v[134:137], v0 offset:1024
	ds_read_b128 v[138:141], v0 offset:2048
	ds_read_b128 v[142:145], v0 offset:3072
	v_add_u32_e32 v0, s65, v175
	ds_read_b128 v[168:171], v0
	ds_read_b128 v[200:203], v0 offset:1024
	ds_read_b128 v[204:207], v0 offset:2048
	ds_read_b128 v[208:211], v0 offset:3072
	s_add_u32 s26, s26, 0x40000
	s_addc_u32 s27, s27, 0
	s_mov_b32 m0, s52
	v_lshl_add_u64 v[244:245], s[26:27], 0, v[160:161]
	ds_read_b128 v[212:215], v177 offset:32768
	ds_read_b128 v[216:219], v177 offset:33792
	ds_read_b128 v[220:223], v177 offset:34816
	ds_read_b128 v[224:227], v177 offset:35840
	ds_read_b128 v[228:231], v177 offset:36864
	ds_read_b128 v[232:235], v177 offset:37888
	ds_read_b128 v[236:239], v177 offset:38912
	ds_read_b128 v[240:243], v177 offset:39936
	global_load_lds_dwordx4 v[244:245], off
	v_lshl_add_u64 v[244:245], s[26:27], 0, v[156:157]
	s_mov_b32 m0, s53
	s_nop 0
	global_load_lds_dwordx4 v[244:245], off
	s_waitcnt vmcnt(8)
	s_waitcnt lgkmcnt(0)
	s_barrier
	s_setprio 1
	s_waitcnt lgkmcnt(0)
	v_mfma_f32_16x16x32_bf16 v[126:129], v[130:133], v[212:215], v[126:129]
	v_mfma_f32_16x16x32_bf16 v[122:125], v[138:141], v[212:215], v[122:125]
	v_mfma_f32_16x16x32_bf16 v[114:117], v[130:133], v[220:223], v[114:117]
	v_mfma_f32_16x16x32_bf16 v[106:109], v[138:141], v[220:223], v[106:109]
	v_mfma_f32_16x16x32_bf16 v[94:97], v[130:133], v[228:231], v[94:97]
	v_mfma_f32_16x16x32_bf16 v[90:93], v[138:141], v[228:231], v[90:93]
	v_mfma_f32_16x16x32_bf16 v[82:85], v[130:133], v[236:239], v[82:85]
	v_mfma_f32_16x16x32_bf16 v[74:77], v[138:141], v[236:239], v[74:77]
	v_mfma_f32_16x16x32_bf16 v[126:129], v[134:137], v[216:219], v[126:129]
	v_mfma_f32_16x16x32_bf16 v[122:125], v[142:145], v[216:219], v[122:125]
	v_mfma_f32_16x16x32_bf16 v[114:117], v[134:137], v[224:227], v[114:117]
	v_mfma_f32_16x16x32_bf16 v[106:109], v[142:145], v[224:227], v[106:109]
	v_mfma_f32_16x16x32_bf16 v[94:97], v[134:137], v[232:235], v[94:97]
	v_mfma_f32_16x16x32_bf16 v[90:93], v[142:145], v[232:235], v[90:93]
	v_mfma_f32_16x16x32_bf16 v[82:85], v[134:137], v[240:243], v[82:85]
	v_mfma_f32_16x16x32_bf16 v[74:77], v[142:145], v[240:243], v[74:77]
	s_setprio 0
	s_setprio 1
	v_mfma_f32_16x16x32_bf16 v[118:121], v[168:171], v[212:215], v[118:121]
	v_mfma_f32_16x16x32_bf16 v[110:113], v[204:207], v[212:215], v[110:113]
	v_mfma_f32_16x16x32_bf16 v[102:105], v[168:171], v[220:223], v[102:105]
	v_mfma_f32_16x16x32_bf16 v[98:101], v[204:207], v[220:223], v[98:101]
	v_mfma_f32_16x16x32_bf16 v[86:89], v[168:171], v[228:231], v[86:89]
	v_mfma_f32_16x16x32_bf16 v[78:81], v[204:207], v[228:231], v[78:81]
	v_mfma_f32_16x16x32_bf16 v[70:73], v[168:171], v[236:239], v[70:73]
	v_mfma_f32_16x16x32_bf16 v[66:69], v[204:207], v[236:239], v[66:69]
	v_mfma_f32_16x16x32_bf16 v[118:121], v[200:203], v[216:219], v[118:121]
	v_mfma_f32_16x16x32_bf16 v[110:113], v[208:211], v[216:219], v[110:113]
	v_mfma_f32_16x16x32_bf16 v[102:105], v[200:203], v[224:227], v[102:105]
	v_mfma_f32_16x16x32_bf16 v[98:101], v[208:211], v[224:227], v[98:101]
	v_mfma_f32_16x16x32_bf16 v[86:89], v[200:203], v[232:235], v[86:89]
	v_mfma_f32_16x16x32_bf16 v[78:81], v[208:211], v[232:235], v[78:81]
	v_mfma_f32_16x16x32_bf16 v[70:73], v[200:203], v[240:243], v[70:73]
	v_mfma_f32_16x16x32_bf16 v[66:69], v[208:211], v[240:243], v[66:69]
	s_setprio 0
	s_barrier
; #define PG8_STAGE(bufoff, gbase, voff) do { _Pragma("unroll") for (int _i = 0; _i < 2; ++_i) \
;         __builtin_amdgcn_global_load_lds((const unsigned*)((const char*)(gbase) + (voff)[_i]), (PG8_LAS unsigned*)(lds + (bufoff) + ldsw + _i * 8192), 16, 0, 0); } while (0)
; #define PG8_LDA(dst, b, h) do { _Pragma("unroll") for (int m = 0; m < 4; ++m) _Pragma("unroll") for (int k = 0; k < 2; ++k) dst[m][k] = *(const PG8_LAS bf16x8*)(lds + PG8_SA(b, h) + aoff + m * 2048 + k * 1024); } while (0)
; #define PG8_MMA(ai, bj, At, Bt) do { __builtin_amdgcn_s_setprio(1); _Pragma("unroll") for (int m = 0; m < 4; ++m) _Pragma("unroll") for (int n = 0; n < 2; ++n) _Pragma("unroll") for (int k = 0; k < 2; ++k) \
;         acc[ai][bj][m][n] = __builtin_amdgcn_mfma_f32_16x16x32_bf16(Bt[n][k], At[m][k], acc[ai][bj][m][n], 0, 0, 0); __builtin_amdgcn_s_setprio(0); } while (0)
; #define PG8_WAIT_V(n) asm volatile("s_waitcnt vmcnt(" #n ")" ::: "memory")
; #define PG8_WAIT_L(n) asm volatile("s_waitcnt lgkmcnt(" #n ")" ::: "memory")
; #define PG8_BAR __builtin_amdgcn_s_barrier()
; #define PG8_SCHED __builtin_amdgcn_sched_barrier(0)
; template <class Epi, class Sched, bool ALIGN_EPI = false, bool SP2 = false>
; __device__ __forceinline__ void gemm_phase(PG8_LAS unsigned char* lds, const Gemm g, const Sched& S, const Epi& E) {
;     ...
;         for (int t = 0; t < nt; t += 2) {
;             const bool last = (t == nt - 2);
;             const char* a1 = cA + (size_t)(t + 1) * kstep;
;             const char* a2 = last ? nA : cA + (size_t)(t + 2) * kstep; const char* b2 = last ? nB : cB + (size_t)(t + 2) * kstep;
;             const char* a3 = a2 + kstep; const char* b3 = b2 + kstep;
;             if (last && has_next) S.a_ready(nxt);
;     ...
;             PG8_WAIT_V(8); PG8_WAIT_L(0); PG8_BAR; PG8_MMA(0, 0, At, B0); PG8_MMA(0, 1, At, B1); PG8_BAR; PG8_SCHED;
;             PG8_LDA(At, 1, 1); PG8_STAGE(PG8_SB(1, 0), b3, voffB); PG8_STAGE(PG8_SB(1, 1), b3 + hstep, voffB); PG8_STAGE(PG8_SA(1, 0), a3, voffA);
;             PG8_WAIT_V(8); PG8_WAIT_L(0); PG8_BAR; PG8_MMA(1, 0, At, B0); PG8_MMA(1, 1, At, B1); PG8_BAR; PG8_SCHED;
	s_add_i32 s26, s64, s30
	v_lshl_add_u64 v[146:147], v[146:147], 0, s[38:39]
	s_mov_b32 m0, s26
	ds_read_b128 v[212:215], v177 offset:49152
	ds_read_b128 v[216:219], v177 offset:50176
	ds_read_b128 v[220:223], v177 offset:51200
	ds_read_b128 v[224:227], v177 offset:52224
	ds_read_b128 v[228:231], v177 offset:53248
	ds_read_b128 v[232:235], v177 offset:54272
	ds_read_b128 v[236:239], v177 offset:55296
	ds_read_b128 v[240:243], v177 offset:56320
	global_load_lds_dwordx4 v[146:147], off
	s_add_i32 m0, s26, 0x2000
	s_add_u32 s24, s24, 0x40080
	v_lshl_add_u64 v[146:147], v[148:149], 0, s[38:39]
	s_addc_u32 s25, s25, 0
	s_add_i32 s26, s65, s30
	global_load_lds_dwordx4 v[146:147], off
	v_lshl_add_u64 v[146:147], s[24:25], 0, v[158:159]
	s_mov_b32 m0, s26
	s_nop 0
	global_load_lds_dwordx4 v[146:147], off
	v_lshl_add_u64 v[146:147], s[24:25], 0, v[154:155]
	s_add_i32 m0, s26, 0x2000
	s_nop 0
	global_load_lds_dwordx4 v[146:147], off
	v_lshl_add_u64 v[146:147], v[172:173], 0, s[38:39]
	s_mov_b32 m0, s55
	s_nop 0
	global_load_lds_dwordx4 v[146:147], off
	v_lshl_add_u64 v[146:147], v[180:181], 0, s[38:39]
	s_mov_b32 m0, s56
	s_nop 0
	global_load_lds_dwordx4 v[146:147], off
	s_waitcnt vmcnt(8)
	s_waitcnt lgkmcnt(0)
	s_barrier
	s_setprio 1
	s_waitcnt lgkmcnt(0)
	v_mfma_f32_16x16x32_bf16 v[62:65], v[130:133], v[212:215], v[62:65]
	v_mfma_f32_16x16x32_bf16 v[58:61], v[138:141], v[212:215], v[58:61]
	v_mfma_f32_16x16x32_bf16 v[50:53], v[130:133], v[220:223], v[50:53]
	v_mfma_f32_16x16x32_bf16 v[42:45], v[138:141], v[220:223], v[42:45]
	v_mfma_f32_16x16x32_bf16 v[30:33], v[130:133], v[228:231], v[30:33]
	v_mfma_f32_16x16x32_bf16 v[26:29], v[138:141], v[228:231], v[26:29]
	v_mfma_f32_16x16x32_bf16 v[18:21], v[130:133], v[236:239], v[18:21]
	v_mfma_f32_16x16x32_bf16 v[10:13], v[138:141], v[236:239], v[10:13]
	v_mfma_f32_16x16x32_bf16 v[62:65], v[134:137], v[216:219], v[62:65]
	v_mfma_f32_16x16x32_bf16 v[58:61], v[142:145], v[216:219], v[58:61]
	v_mfma_f32_16x16x32_bf16 v[50:53], v[134:137], v[224:227], v[50:53]
	v_mfma_f32_16x16x32_bf16 v[42:45], v[142:145], v[224:227], v[42:45]
	v_mfma_f32_16x16x32_bf16 v[30:33], v[134:137], v[232:235], v[30:33]
	v_mfma_f32_16x16x32_bf16 v[26:29], v[142:145], v[232:235], v[26:29]
	v_mfma_f32_16x16x32_bf16 v[18:21], v[134:137], v[240:243], v[18:21]
	v_mfma_f32_16x16x32_bf16 v[10:13], v[142:145], v[240:243], v[10:13]
	s_setprio 0
	s_setprio 1
	v_mfma_f32_16x16x32_bf16 v[54:57], v[168:171], v[212:215], v[54:57]
	v_mfma_f32_16x16x32_bf16 v[46:49], v[204:207], v[212:215], v[46:49]
	v_mfma_f32_16x16x32_bf16 v[38:41], v[168:171], v[220:223], v[38:41]
	v_mfma_f32_16x16x32_bf16 v[34:37], v[204:207], v[220:223], v[34:37]
	v_mfma_f32_16x16x32_bf16 v[22:25], v[168:171], v[228:231], v[22:25]
	v_mfma_f32_16x16x32_bf16 v[14:17], v[204:207], v[228:231], v[14:17]
	v_mfma_f32_16x16x32_bf16 v[6:9], v[168:171], v[236:239], v[6:9]
	v_mfma_f32_16x16x32_bf16 v[2:5], v[204:207], v[236:239], v[2:5]
	v_mfma_f32_16x16x32_bf16 v[54:57], v[200:203], v[216:219], v[54:57]
	v_mfma_f32_16x16x32_bf16 v[46:49], v[208:211], v[216:219], v[46:49]
	v_mfma_f32_16x16x32_bf16 v[38:41], v[200:203], v[224:227], v[38:41]
	v_mfma_f32_16x16x32_bf16 v[34:37], v[208:211], v[224:227], v[34:37]
	v_mfma_f32_16x16x32_bf16 v[22:25], v[200:203], v[232:235], v[22:25]
	v_mfma_f32_16x16x32_bf16 v[14:17], v[208:211], v[232:235], v[14:17]
	v_mfma_f32_16x16x32_bf16 v[6:9], v[200:203], v[240:243], v[6:9]
	v_mfma_f32_16x16x32_bf16 v[2:5], v[208:211], v[240:243], v[2:5]
	s_setprio 0
	s_add_i32 s63, s63, 2
	s_add_u32 s22, s22, 0x100
	s_addc_u32 s23, s23, 0
	s_add_u32 s61, s61, 0x100
	s_addc_u32 s62, s62, 0
	s_add_u32 s24, s22, 0xfffc0080
	s_addc_u32 s25, s23, -1
	s_add_i32 s64, 0, 0x10000
	s_cmp_eq_u32 s63, 12
	s_cselect_b32 s27, s15, s25
	s_cselect_b32 s26, s21, s24
	s_cselect_b32 s25, s13, s62
	s_cselect_b32 s24, s60, s61
	s_add_i32 s66, 0, 0x14000
	s_barrier
	s_cmp_gt_u32 s63, 13
	s_cbranch_scc0 .Lrot_558
	s_and_b64 vcc, exec, s[8:9]
	s_cbranch_vccnz .LBB0_563
	v_lshl_add_u32 v168, s20, 8, v174
	s_cmp_ge_i32 s59, s54
	s_mov_b64 s[20:21], -1
	s_cbranch_scc1 .LBB0_564

; #define PG8_STAGE(bufoff, gbase, voff) do { _Pragma("unroll") for (int _i = 0; _i < 2; ++_i) \
;         __builtin_amdgcn_global_load_lds((const unsigned*)((const char*)(gbase) + (voff)[_i]), (PG8_LAS unsigned*)(lds + (bufoff) + ldsw + _i * 8192), 16, 0, 0); } while (0)
; #define PG8_LDA(dst, b, h) do { _Pragma("unroll") for (int m = 0; m < 4; ++m) _Pragma("unroll") for (int k = 0; k < 2; ++k) dst[m][k] = *(const PG8_LAS bf16x8*)(lds + PG8_SA(b, h) + aoff + m * 2048 + k * 1024); } while (0)
; #define PG8_LDB(dst, b, h) do { _Pragma("unroll") for (int n = 0; n < 2; ++n) _Pragma("unroll") for (int k = 0; k < 2; ++k) dst[n][k] = *(const PG8_LAS bf16x8*)(lds + PG8_SB(b, h) + boff + n * 2048 + k * 1024); } while (0)
; #define PG8_MMA(ai, bj, At, Bt) do { __builtin_amdgcn_s_setprio(1); _Pragma("unroll") for (int m = 0; m < 4; ++m) _Pragma("unroll") for (int n = 0; n < 2; ++n) _Pragma("unroll") for (int k = 0; k < 2; ++k) \
;         acc[ai][bj][m][n] = __builtin_amdgcn_mfma_f32_16x16x32_bf16(Bt[n][k], At[m][k], acc[ai][bj][m][n], 0, 0, 0); __builtin_amdgcn_s_setprio(0); } while (0)
; #define PG8_WAIT_V(n) asm volatile("s_waitcnt vmcnt(" #n ")" ::: "memory")
; #define PG8_WAIT_L(n) asm volatile("s_waitcnt lgkmcnt(" #n ")" ::: "memory")
; #define PG8_BAR __builtin_amdgcn_s_barrier()
; #define PG8_SCHED __builtin_amdgcn_sched_barrier(0)
; template <class Epi, class Sched, bool ALIGN_EPI = false, bool SP2 = false>
; __device__ __forceinline__ void gemm_phase(PG8_LAS unsigned char* lds, const Gemm g, const Sched& S, const Epi& E) {
;     ...
;         for (int t = 0; t < nt; t += 2) {
;             const bool last = (t == nt - 2);
;             const char* a1 = cA + (size_t)(t + 1) * kstep;
;             const char* a2 = last ? nA : cA + (size_t)(t + 2) * kstep; const char* b2 = last ? nB : cB + (size_t)(t + 2) * kstep;
;             const char* a3 = a2 + kstep; const char* b3 = b2 + kstep;
;             if (last && has_next) S.a_ready(nxt);
;             if constexpr (SP2) {
;             PG8_LDB(B0, 0, 0); PG8_LDB(B1, 0, 1); PG8_SCHED; PG8_LDA(At, 0, 0); PG8_STAGE(PG8_SA(1, 1), a1 + hstep, voffA);
;             PG8_WAIT_V(8); PG8_WAIT_L(0); PG8_BAR; PG8_MMA(0, 0, At, B0); PG8_MMA(0, 1, At, B1); PG8_BAR; PG8_SCHED;
.LBB0_1090:
	s_add_u32 s18, s16, 0xfffc0080
	s_addc_u32 s19, s17, -1
	s_add_i32 s50, 0, 0x10000
	s_cmp_eq_u32 s49, 12
	s_cselect_b32 s21, s11, s19
	s_cselect_b32 s20, s45, s18
	s_cselect_b32 s19, s9, s48
	s_cselect_b32 s18, s46, s47
	s_add_i32 s52, 0, 0x14000
.Lrot_1090:
	v_add_u32_e32 v148, s50, v167
	ds_read_b128 v[140:143], v148
	ds_read_b128 v[144:147], v148 offset:1024
	ds_read_b128 v[154:157], v148 offset:2048
	ds_read_b128 v[158:161], v148 offset:3072
	v_add_u32_e32 v148, s52, v167
	ds_read_b128 v[162:165], v148
	ds_read_b128 v[170:173], v148 offset:1024
	ds_read_b128 v[174:177], v148 offset:2048
	ds_read_b128 v[178:181], v148 offset:3072
	v_lshl_add_u64 v[148:149], s[16:17], 0, v[136:137]
	s_add_i32 m0, s25, 0xc000
	ds_read_b128 v[200:203], v169
	ds_read_b128 v[204:207], v169 offset:1024
	ds_read_b128 v[208:211], v169 offset:2048
	ds_read_b128 v[212:215], v169 offset:3072
	ds_read_b128 v[216:219], v169 offset:4096
	ds_read_b128 v[220:223], v169 offset:5120
	ds_read_b128 v[224:227], v169 offset:6144
	ds_read_b128 v[228:231], v169 offset:7168
	global_load_lds_dwordx4 v[148:149], off
	v_lshl_add_u64 v[148:149], s[16:17], 0, v[138:139]
	s_add_i32 m0, s25, 0xe000
	s_nop 0
	global_load_lds_dwordx4 v[148:149], off
	s_waitcnt vmcnt(8)
	s_waitcnt lgkmcnt(0)
	s_barrier
	s_setprio 1
	s_waitcnt lgkmcnt(0)
	v_mfma_f32_16x16x32_bf16 v[126:129], v[140:143], v[200:203], v[126:129]
	v_mfma_f32_16x16x32_bf16 v[122:125], v[154:157], v[200:203], v[122:125]
	v_mfma_f32_16x16x32_bf16 v[118:121], v[140:143], v[208:211], v[118:121]
	v_mfma_f32_16x16x32_bf16 v[114:117], v[154:157], v[208:211], v[114:117]
	v_mfma_f32_16x16x32_bf16 v[110:113], v[140:143], v[216:219], v[110:113]
	v_mfma_f32_16x16x32_bf16 v[106:109], v[154:157], v[216:219], v[106:109]
	v_mfma_f32_16x16x32_bf16 v[102:105], v[140:143], v[224:227], v[102:105]
	v_mfma_f32_16x16x32_bf16 v[98:101], v[154:157], v[224:227], v[98:101]
	v_mfma_f32_16x16x32_bf16 v[126:129], v[144:147], v[204:207], v[126:129]
	v_mfma_f32_16x16x32_bf16 v[122:125], v[158:161], v[204:207], v[122:125]
	v_mfma_f32_16x16x32_bf16 v[118:121], v[144:147], v[212:215], v[118:121]
	v_mfma_f32_16x16x32_bf16 v[114:117], v[158:161], v[212:215], v[114:117]
	v_mfma_f32_16x16x32_bf16 v[110:113], v[144:147], v[220:223], v[110:113]
	v_mfma_f32_16x16x32_bf16 v[106:109], v[158:161], v[220:223], v[106:109]
	v_mfma_f32_16x16x32_bf16 v[102:105], v[144:147], v[228:231], v[102:105]
	v_mfma_f32_16x16x32_bf16 v[98:101], v[158:161], v[228:231], v[98:101]
	s_setprio 0
	s_setprio 1
	v_mfma_f32_16x16x32_bf16 v[62:65], v[162:165], v[200:203], v[62:65]
	v_mfma_f32_16x16x32_bf16 v[58:61], v[174:177], v[200:203], v[58:61]
	v_mfma_f32_16x16x32_bf16 v[54:57], v[162:165], v[208:211], v[54:57]
	v_mfma_f32_16x16x32_bf16 v[50:53], v[174:177], v[208:211], v[50:53]
	v_mfma_f32_16x16x32_bf16 v[46:49], v[162:165], v[216:219], v[46:49]
	v_mfma_f32_16x16x32_bf16 v[42:45], v[174:177], v[216:219], v[42:45]
	v_mfma_f32_16x16x32_bf16 v[38:41], v[162:165], v[224:227], v[38:41]
	v_mfma_f32_16x16x32_bf16 v[34:37], v[174:177], v[224:227], v[34:37]
	v_mfma_f32_16x16x32_bf16 v[62:65], v[170:173], v[204:207], v[62:65]
	v_mfma_f32_16x16x32_bf16 v[58:61], v[178:181], v[204:207], v[58:61]
	v_mfma_f32_16x16x32_bf16 v[54:57], v[170:173], v[212:215], v[54:57]
	v_mfma_f32_16x16x32_bf16 v[50:53], v[178:181], v[212:215], v[50:53]
	v_mfma_f32_16x16x32_bf16 v[46:49], v[170:173], v[220:223], v[46:49]
	v_mfma_f32_16x16x32_bf16 v[42:45], v[178:181], v[220:223], v[42:45]
	v_mfma_f32_16x16x32_bf16 v[38:41], v[170:173], v[228:231], v[38:41]
	v_mfma_f32_16x16x32_bf16 v[34:37], v[178:181], v[228:231], v[34:37]
	s_setprio 0
	s_barrier
	s_add_i32 s50, s50, s24
	v_lshl_add_u64 v[148:149], s[18:19], 0, v[0:1]
	s_mov_b32 m0, s50
	ds_read_b128 v[200:203], v169 offset:16384
	ds_read_b128 v[204:207], v169 offset:17408
	ds_read_b128 v[208:211], v169 offset:18432
	ds_read_b128 v[212:215], v169 offset:19456
	ds_read_b128 v[216:219], v169 offset:20480
	ds_read_b128 v[220:223], v169 offset:21504
	ds_read_b128 v[224:227], v169 offset:22528
	ds_read_b128 v[228:231], v169 offset:23552
	global_load_lds_dwordx4 v[148:149], off
	s_add_i32 m0, s50, 0x2000
	s_add_u32 s50, s18, 0x40000
	v_lshl_add_u64 v[232:233], s[18:19], 0, v[130:131]
	s_addc_u32 s51, s19, 0
	s_add_i32 s52, s52, s24
	global_load_lds_dwordx4 v[232:233], off
	v_lshl_add_u64 v[234:235], s[50:51], 0, v[0:1]
	s_mov_b32 m0, s52
	v_lshl_add_u64 v[236:237], s[20:21], 0, v[132:133]
	global_load_lds_dwordx4 v[234:235], off
	v_lshl_add_u64 v[234:235], s[50:51], 0, v[130:131]
	s_add_i32 m0, s52, 0x2000
	s_nop 0
	global_load_lds_dwordx4 v[234:235], off
	v_lshl_add_u64 v[234:235], s[20:21], 0, v[134:135]
	s_mov_b32 m0, s25
	s_nop 0
	global_load_lds_dwordx4 v[234:235], off
	s_mov_b32 m0, s26
	s_nop 0
	global_load_lds_dwordx4 v[236:237], off
	s_waitcnt vmcnt(8)
	s_waitcnt lgkmcnt(0)
	s_barrier
; #define PG8_STAGE(bufoff, gbase, voff) do { _Pragma("unroll") for (int _i = 0; _i < 2; ++_i) \
;         __builtin_amdgcn_global_load_lds((const unsigned*)((const char*)(gbase) + (voff)[_i]), (PG8_LAS unsigned*)(lds + (bufoff) + ldsw + _i * 8192), 16, 0, 0); } while (0)
; #define PG8_LDA(dst, b, h) do { _Pragma("unroll") for (int m = 0; m < 4; ++m) _Pragma("unroll") for (int k = 0; k < 2; ++k) dst[m][k] = *(const PG8_LAS bf16x8*)(lds + PG8_SA(b, h) + aoff + m * 2048 + k * 1024); } while (0)
; #define PG8_LDB(dst, b, h) do { _Pragma("unroll") for (int n = 0; n < 2; ++n) _Pragma("unroll") for (int k = 0; k < 2; ++k) dst[n][k] = *(const PG8_LAS bf16x8*)(lds + PG8_SB(b, h) + boff + n * 2048 + k * 1024); } while (0)
; #define PG8_MMA(ai, bj, At, Bt) do { __builtin_amdgcn_s_setprio(1); _Pragma("unroll") for (int m = 0; m < 4; ++m) _Pragma("unroll") for (int n = 0; n < 2; ++n) _Pragma("unroll") for (int k = 0; k < 2; ++k) \
;         acc[ai][bj][m][n] = __builtin_amdgcn_mfma_f32_16x16x32_bf16(Bt[n][k], At[m][k], acc[ai][bj][m][n], 0, 0, 0); __builtin_amdgcn_s_setprio(0); } while (0)
; #define PG8_WAIT_V(n) asm volatile("s_waitcnt vmcnt(" #n ")" ::: "memory")
; #define PG8_WAIT_L(n) asm volatile("s_waitcnt lgkmcnt(" #n ")" ::: "memory")
; #define PG8_BAR __builtin_amdgcn_s_barrier()
; #define PG8_SCHED __builtin_amdgcn_sched_barrier(0)
; template <class Epi, class Sched, bool ALIGN_EPI = false, bool SP2 = false>
; __device__ __forceinline__ void gemm_phase(PG8_LAS unsigned char* lds, const Gemm g, const Sched& S, const Epi& E) {
;     ...
;             PG8_WAIT_V(8); PG8_WAIT_L(0); PG8_BAR; PG8_MMA(0, 0, At, B0); PG8_MMA(0, 1, At, B1); PG8_BAR; PG8_SCHED;
;             PG8_LDA(At, 0, 1); PG8_STAGE(PG8_SB(0, 0), b2, voffB); PG8_STAGE(PG8_SB(0, 1), b2 + hstep, voffB); PG8_STAGE(PG8_SA(0, 0), a2, voffA);
;             PG8_WAIT_V(8); PG8_WAIT_L(0); PG8_BAR; PG8_MMA(1, 0, At, B0); PG8_MMA(1, 1, At, B1); PG8_BAR; PG8_SCHED;
;             PG8_LDB(B0, 1, 0); PG8_LDB(B1, 1, 1); PG8_SCHED; PG8_LDA(At, 1, 0); PG8_STAGE(PG8_SA(0, 1), a2 + hstep, voffA);
;             PG8_WAIT_V(8); PG8_WAIT_L(0); PG8_BAR; PG8_MMA(0, 0, At, B0); PG8_MMA(0, 1, At, B1); PG8_BAR; PG8_SCHED;
	s_setprio 1
	s_waitcnt lgkmcnt(0)
	v_mfma_f32_16x16x32_bf16 v[94:97], v[140:143], v[200:203], v[94:97]
	v_mfma_f32_16x16x32_bf16 v[90:93], v[154:157], v[200:203], v[90:93]
	v_mfma_f32_16x16x32_bf16 v[86:89], v[140:143], v[208:211], v[86:89]
	v_mfma_f32_16x16x32_bf16 v[82:85], v[154:157], v[208:211], v[82:85]
	v_mfma_f32_16x16x32_bf16 v[78:81], v[140:143], v[216:219], v[78:81]
	v_mfma_f32_16x16x32_bf16 v[74:77], v[154:157], v[216:219], v[74:77]
	v_mfma_f32_16x16x32_bf16 v[70:73], v[140:143], v[224:227], v[70:73]
	v_mfma_f32_16x16x32_bf16 v[66:69], v[154:157], v[224:227], v[66:69]
	v_mfma_f32_16x16x32_bf16 v[94:97], v[144:147], v[204:207], v[94:97]
	v_mfma_f32_16x16x32_bf16 v[90:93], v[158:161], v[204:207], v[90:93]
	v_mfma_f32_16x16x32_bf16 v[86:89], v[144:147], v[212:215], v[86:89]
	v_mfma_f32_16x16x32_bf16 v[82:85], v[158:161], v[212:215], v[82:85]
	v_mfma_f32_16x16x32_bf16 v[78:81], v[144:147], v[220:223], v[78:81]
	v_mfma_f32_16x16x32_bf16 v[74:77], v[158:161], v[220:223], v[74:77]
	v_mfma_f32_16x16x32_bf16 v[70:73], v[144:147], v[228:231], v[70:73]
	v_mfma_f32_16x16x32_bf16 v[66:69], v[158:161], v[228:231], v[66:69]
	s_setprio 0
	s_setprio 1
	v_mfma_f32_16x16x32_bf16 v[30:33], v[162:165], v[200:203], v[30:33]
	v_mfma_f32_16x16x32_bf16 v[26:29], v[174:177], v[200:203], v[26:29]
	v_mfma_f32_16x16x32_bf16 v[22:25], v[162:165], v[208:211], v[22:25]
	v_mfma_f32_16x16x32_bf16 v[18:21], v[174:177], v[208:211], v[18:21]
	v_mfma_f32_16x16x32_bf16 v[14:17], v[162:165], v[216:219], v[14:17]
	v_mfma_f32_16x16x32_bf16 v[10:13], v[174:177], v[216:219], v[10:13]
	v_mfma_f32_16x16x32_bf16 v[6:9], v[162:165], v[224:227], v[6:9]
	v_mfma_f32_16x16x32_bf16 v[2:5], v[174:177], v[224:227], v[2:5]
	v_mfma_f32_16x16x32_bf16 v[30:33], v[170:173], v[204:207], v[30:33]
	v_mfma_f32_16x16x32_bf16 v[26:29], v[178:181], v[204:207], v[26:29]
	v_mfma_f32_16x16x32_bf16 v[22:25], v[170:173], v[212:215], v[22:25]
	v_mfma_f32_16x16x32_bf16 v[18:21], v[178:181], v[212:215], v[18:21]
	v_mfma_f32_16x16x32_bf16 v[14:17], v[170:173], v[220:223], v[14:17]
	v_mfma_f32_16x16x32_bf16 v[10:13], v[178:181], v[220:223], v[10:13]
	v_mfma_f32_16x16x32_bf16 v[6:9], v[170:173], v[228:231], v[6:9]
	v_mfma_f32_16x16x32_bf16 v[2:5], v[178:181], v[228:231], v[2:5]
	s_setprio 0
	s_barrier
	s_add_i32 s50, 0, 0x18000
	s_add_i32 s51, 0, 0x1c000
	v_add_u32_e32 v158, s50, v167
	v_add_u32_e32 v178, s51, v167
	ds_read_b128 v[140:143], v158
	ds_read_b128 v[144:147], v158 offset:1024
	ds_read_b128 v[154:157], v158 offset:2048
	ds_read_b128 v[158:161], v158 offset:3072
	ds_read_b128 v[162:165], v178
	ds_read_b128 v[170:173], v178 offset:1024
	ds_read_b128 v[174:177], v178 offset:2048
	ds_read_b128 v[178:181], v178 offset:3072
	s_add_u32 s20, s20, 0x40000
	s_addc_u32 s21, s21, 0
	s_mov_b32 m0, s27
	v_lshl_add_u64 v[238:239], s[20:21], 0, v[134:135]
	ds_read_b128 v[200:203], v169 offset:32768
	ds_read_b128 v[204:207], v169 offset:33792
	ds_read_b128 v[208:211], v169 offset:34816
	ds_read_b128 v[212:215], v169 offset:35840
	ds_read_b128 v[216:219], v169 offset:36864
	ds_read_b128 v[220:223], v169 offset:37888
	ds_read_b128 v[224:227], v169 offset:38912
	ds_read_b128 v[228:231], v169 offset:39936
	global_load_lds_dwordx4 v[238:239], off
	v_lshl_add_u64 v[238:239], s[20:21], 0, v[132:133]
	s_mov_b32 m0, s28
	s_nop 0
	global_load_lds_dwordx4 v[238:239], off
	s_waitcnt vmcnt(8)
	s_waitcnt lgkmcnt(0)
	s_barrier
	s_setprio 1
	s_waitcnt lgkmcnt(0)
	v_mfma_f32_16x16x32_bf16 v[126:129], v[140:143], v[200:203], v[126:129]
	v_mfma_f32_16x16x32_bf16 v[122:125], v[154:157], v[200:203], v[122:125]
	v_mfma_f32_16x16x32_bf16 v[118:121], v[140:143], v[208:211], v[118:121]
	v_mfma_f32_16x16x32_bf16 v[114:117], v[154:157], v[208:211], v[114:117]
	v_mfma_f32_16x16x32_bf16 v[110:113], v[140:143], v[216:219], v[110:113]
	v_mfma_f32_16x16x32_bf16 v[106:109], v[154:157], v[216:219], v[106:109]
	v_mfma_f32_16x16x32_bf16 v[102:105], v[140:143], v[224:227], v[102:105]
	v_mfma_f32_16x16x32_bf16 v[98:101], v[154:157], v[224:227], v[98:101]
	v_mfma_f32_16x16x32_bf16 v[126:129], v[144:147], v[204:207], v[126:129]
	v_mfma_f32_16x16x32_bf16 v[122:125], v[158:161], v[204:207], v[122:125]
	v_mfma_f32_16x16x32_bf16 v[118:121], v[144:147], v[212:215], v[118:121]
	v_mfma_f32_16x16x32_bf16 v[114:117], v[158:161], v[212:215], v[114:117]
	v_mfma_f32_16x16x32_bf16 v[110:113], v[144:147], v[220:223], v[110:113]
	v_mfma_f32_16x16x32_bf16 v[106:109], v[158:161], v[220:223], v[106:109]
	v_mfma_f32_16x16x32_bf16 v[102:105], v[144:147], v[228:231], v[102:105]
	v_mfma_f32_16x16x32_bf16 v[98:101], v[158:161], v[228:231], v[98:101]
	s_setprio 0
	s_setprio 1
	v_mfma_f32_16x16x32_bf16 v[62:65], v[162:165], v[200:203], v[62:65]
	v_mfma_f32_16x16x32_bf16 v[58:61], v[174:177], v[200:203], v[58:61]
	v_mfma_f32_16x16x32_bf16 v[54:57], v[162:165], v[208:211], v[54:57]
	v_mfma_f32_16x16x32_bf16 v[50:53], v[174:177], v[208:211], v[50:53]
	v_mfma_f32_16x16x32_bf16 v[46:49], v[162:165], v[216:219], v[46:49]
	v_mfma_f32_16x16x32_bf16 v[42:45], v[174:177], v[216:219], v[42:45]
	v_mfma_f32_16x16x32_bf16 v[38:41], v[162:165], v[224:227], v[38:41]
	v_mfma_f32_16x16x32_bf16 v[34:37], v[174:177], v[224:227], v[34:37]
	v_mfma_f32_16x16x32_bf16 v[62:65], v[170:173], v[204:207], v[62:65]
	v_mfma_f32_16x16x32_bf16 v[58:61], v[178:181], v[204:207], v[58:61]
	v_mfma_f32_16x16x32_bf16 v[54:57], v[170:173], v[212:215], v[54:57]
	v_mfma_f32_16x16x32_bf16 v[50:53], v[178:181], v[212:215], v[50:53]
	v_mfma_f32_16x16x32_bf16 v[46:49], v[170:173], v[220:223], v[46:49]
	v_mfma_f32_16x16x32_bf16 v[42:45], v[178:181], v[220:223], v[42:45]
	v_mfma_f32_16x16x32_bf16 v[38:41], v[170:173], v[228:231], v[38:41]
	v_mfma_f32_16x16x32_bf16 v[34:37], v[178:181], v[228:231], v[34:37]
	s_setprio 0
	s_barrier
; #define PG8_STAGE(bufoff, gbase, voff) do { _Pragma("unroll") for (int _i = 0; _i < 2; ++_i) \
;         __builtin_amdgcn_global_load_lds((const unsigned*)((const char*)(gbase) + (voff)[_i]), (PG8_LAS unsigned*)(lds + (bufoff) + ldsw + _i * 8192), 16, 0, 0); } while (0)
; #define PG8_LDA(dst, b, h) do { _Pragma("unroll") for (int m = 0; m < 4; ++m) _Pragma("unroll") for (int k = 0; k < 2; ++k) dst[m][k] = *(const PG8_LAS bf16x8*)(lds + PG8_SA(b, h) + aoff + m * 2048 + k * 1024); } while (0)
; #define PG8_MMA(ai, bj, At, Bt) do { __builtin_amdgcn_s_setprio(1); _Pragma("unroll") for (int m = 0; m < 4; ++m) _Pragma("unroll") for (int n = 0; n < 2; ++n) _Pragma("unroll") for (int k = 0; k < 2; ++k) \
;         acc[ai][bj][m][n] = __builtin_amdgcn_mfma_f32_16x16x32_bf16(Bt[n][k], At[m][k], acc[ai][bj][m][n], 0, 0, 0); __builtin_amdgcn_s_setprio(0); } while (0)
; #define PG8_WAIT_V(n) asm volatile("s_waitcnt vmcnt(" #n ")" ::: "memory")
; #define PG8_WAIT_L(n) asm volatile("s_waitcnt lgkmcnt(" #n ")" ::: "memory")
; #define PG8_BAR __builtin_amdgcn_s_barrier()
; #define PG8_SCHED __builtin_amdgcn_sched_barrier(0)
; template <class Epi, class Sched, bool ALIGN_EPI = false, bool SP2 = false>
; __device__ __forceinline__ void gemm_phase(PG8_LAS unsigned char* lds, const Gemm g, const Sched& S, const Epi& E) {
;     ...
;         for (int t = 0; t < nt; t += 2) {
;             const bool last = (t == nt - 2);
;             const char* a1 = cA + (size_t)(t + 1) * kstep;
;             const char* a2 = last ? nA : cA + (size_t)(t + 2) * kstep; const char* b2 = last ? nB : cB + (size_t)(t + 2) * kstep;
;             const char* a3 = a2 + kstep; const char* b3 = b2 + kstep;
;             if (last && has_next) S.a_ready(nxt);
;     ...
;             PG8_WAIT_V(8); PG8_WAIT_L(0); PG8_BAR; PG8_MMA(0, 0, At, B0); PG8_MMA(0, 1, At, B1); PG8_BAR; PG8_SCHED;
;             PG8_LDA(At, 1, 1); PG8_STAGE(PG8_SB(1, 0), b3, voffB); PG8_STAGE(PG8_SB(1, 1), b3 + hstep, voffB); PG8_STAGE(PG8_SA(1, 0), a3, voffA);
;             PG8_WAIT_V(8); PG8_WAIT_L(0); PG8_BAR; PG8_MMA(1, 0, At, B0); PG8_MMA(1, 1, At, B1); PG8_BAR; PG8_SCHED;
	s_add_i32 s20, s50, s24
	v_lshl_add_u64 v[148:149], v[148:149], 0, s[38:39]
	s_mov_b32 m0, s20
	ds_read_b128 v[200:203], v169 offset:49152
	ds_read_b128 v[204:207], v169 offset:50176
	ds_read_b128 v[208:211], v169 offset:51200
	ds_read_b128 v[212:215], v169 offset:52224
	ds_read_b128 v[216:219], v169 offset:53248
	ds_read_b128 v[220:223], v169 offset:54272
	ds_read_b128 v[224:227], v169 offset:55296
	ds_read_b128 v[228:231], v169 offset:56320
	global_load_lds_dwordx4 v[148:149], off
	s_add_i32 m0, s20, 0x2000
	s_add_u32 s18, s18, 0x40080
	v_lshl_add_u64 v[148:149], v[232:233], 0, s[38:39]
	s_addc_u32 s19, s19, 0
	s_add_i32 s20, s51, s24
	global_load_lds_dwordx4 v[148:149], off
	v_lshl_add_u64 v[148:149], s[18:19], 0, v[0:1]
	s_mov_b32 m0, s20
	s_nop 0
	global_load_lds_dwordx4 v[148:149], off
	v_lshl_add_u64 v[148:149], s[18:19], 0, v[130:131]
	s_add_i32 m0, s20, 0x2000
	s_nop 0
	global_load_lds_dwordx4 v[148:149], off
	v_lshl_add_u64 v[148:149], v[234:235], 0, s[38:39]
	s_mov_b32 m0, s31
	s_nop 0
	global_load_lds_dwordx4 v[148:149], off
	v_lshl_add_u64 v[148:149], v[236:237], 0, s[38:39]
	s_mov_b32 m0, s33
	s_nop 0
	global_load_lds_dwordx4 v[148:149], off
	s_waitcnt vmcnt(8)
	s_waitcnt lgkmcnt(0)
	s_barrier
	s_setprio 1
	s_waitcnt lgkmcnt(0)
	v_mfma_f32_16x16x32_bf16 v[94:97], v[140:143], v[200:203], v[94:97]
	v_mfma_f32_16x16x32_bf16 v[90:93], v[154:157], v[200:203], v[90:93]
	v_mfma_f32_16x16x32_bf16 v[86:89], v[140:143], v[208:211], v[86:89]
	v_mfma_f32_16x16x32_bf16 v[82:85], v[154:157], v[208:211], v[82:85]
	v_mfma_f32_16x16x32_bf16 v[78:81], v[140:143], v[216:219], v[78:81]
	v_mfma_f32_16x16x32_bf16 v[74:77], v[154:157], v[216:219], v[74:77]
	v_mfma_f32_16x16x32_bf16 v[70:73], v[140:143], v[224:227], v[70:73]
	v_mfma_f32_16x16x32_bf16 v[66:69], v[154:157], v[224:227], v[66:69]
	v_mfma_f32_16x16x32_bf16 v[94:97], v[144:147], v[204:207], v[94:97]
	v_mfma_f32_16x16x32_bf16 v[90:93], v[158:161], v[204:207], v[90:93]
	v_mfma_f32_16x16x32_bf16 v[86:89], v[144:147], v[212:215], v[86:89]
	v_mfma_f32_16x16x32_bf16 v[82:85], v[158:161], v[212:215], v[82:85]
	v_mfma_f32_16x16x32_bf16 v[78:81], v[144:147], v[220:223], v[78:81]
	v_mfma_f32_16x16x32_bf16 v[74:77], v[158:161], v[220:223], v[74:77]
	v_mfma_f32_16x16x32_bf16 v[70:73], v[144:147], v[228:231], v[70:73]
	v_mfma_f32_16x16x32_bf16 v[66:69], v[158:161], v[228:231], v[66:69]
	s_setprio 0
	s_setprio 1
	v_mfma_f32_16x16x32_bf16 v[30:33], v[162:165], v[200:203], v[30:33]
	v_mfma_f32_16x16x32_bf16 v[26:29], v[174:177], v[200:203], v[26:29]
	v_mfma_f32_16x16x32_bf16 v[22:25], v[162:165], v[208:211], v[22:25]
	v_mfma_f32_16x16x32_bf16 v[18:21], v[174:177], v[208:211], v[18:21]
	v_mfma_f32_16x16x32_bf16 v[14:17], v[162:165], v[216:219], v[14:17]
	v_mfma_f32_16x16x32_bf16 v[10:13], v[174:177], v[216:219], v[10:13]
	v_mfma_f32_16x16x32_bf16 v[6:9], v[162:165], v[224:227], v[6:9]
	v_mfma_f32_16x16x32_bf16 v[2:5], v[174:177], v[224:227], v[2:5]
	v_mfma_f32_16x16x32_bf16 v[30:33], v[170:173], v[204:207], v[30:33]
	v_mfma_f32_16x16x32_bf16 v[26:29], v[178:181], v[204:207], v[26:29]
	v_mfma_f32_16x16x32_bf16 v[22:25], v[170:173], v[212:215], v[22:25]
	v_mfma_f32_16x16x32_bf16 v[18:21], v[178:181], v[212:215], v[18:21]
	v_mfma_f32_16x16x32_bf16 v[14:17], v[170:173], v[220:223], v[14:17]
	v_mfma_f32_16x16x32_bf16 v[10:13], v[178:181], v[220:223], v[10:13]
	v_mfma_f32_16x16x32_bf16 v[6:9], v[170:173], v[228:231], v[6:9]
	v_mfma_f32_16x16x32_bf16 v[2:5], v[178:181], v[228:231], v[2:5]
	s_setprio 0
	s_add_i32 s49, s49, 2
	s_add_u32 s16, s16, 0x100
	s_addc_u32 s17, s17, 0
	s_add_u32 s47, s47, 0x100
	s_addc_u32 s48, s48, 0
	s_add_u32 s18, s16, 0xfffc0080
	s_addc_u32 s19, s17, -1
	s_add_i32 s50, 0, 0x10000
	s_cmp_eq_u32 s49, 12
	s_cselect_b32 s21, s11, s19
	s_cselect_b32 s20, s45, s18
	s_cselect_b32 s19, s9, s48
	s_cselect_b32 s18, s46, s47
	s_add_i32 s52, 0, 0x14000
	s_barrier
	s_cmp_gt_u32 s49, 13
	s_cbranch_scc0 .Lrot_1090
	s_and_b64 vcc, exec, s[6:7]
	s_cbranch_vccz .LBB0_1093
	s_barrier
